# dense attention: every v_pk_fma_f32 (scale-and-subtract of scores) split into two scalar v_fma_f32, bit-identical
# speedup vs baseline: 1.0049x; 1.0049x over previous
; #define RAW_BARRIER() do { asm volatile("s_waitcnt lgkmcnt(0)" ::: "memory"); __builtin_amdgcn_s_barrier(); } while (0)
; template <int DK, int QB, bool NA>
; DEVI void attn_item(const AttnArgs& a, unsigned char* smem) {
;     ...
;   bf16x8 qf[QB][KS];
; #pragma unroll
;   for (int qb = 0; qb < QB; ++qb) {
;     const bf16_t* qp = a.Q + (size_t)((wact ? w * QB * 16 : 0) + qb * 16 + l16) * a.ldq + g * 8;
; #pragma unroll
;     for (int ks = 0; ks < KS; ++ks) qf[qb][ks] = *(const bf16x8*)(qp + ks * 32);
;   }
;   float m[QB], l[QB];
;   f32x4 o[4][QB];
; #pragma unroll
;   for (int qb = 0; qb < QB; ++qb) {
;     m[qb] = NA ? -1e30f : 0.f; l[qb] = 0.f;
; #pragma unroll
;     for (int db = 0; db < 4; ++db) o[db][qb] = (f32x4){0.f, 0.f, 0.f, 0.f};
;   }
;   const int r8 = tid >> 3, c8 = (tid & 7) ^ ((tid >> 4) & 7);
;   const bf16_t* Kn = a.K + (size_t)r8 * a.ldk + c8 * 8;
;   const bf16_t* Kr = a.K + (size_t)(tid >> 2) * a.ldk + 64 + (((tid & 3) ^ ((0 - (tid >> 4)) & 3)) * 8);
;   const bf16_t* Vg = a.Vt + (size_t)r8 * a.Lk + c8 * 8;
;   const size_t kstep = (size_t)32 * a.ldk, vstep = (size_t)32 * a.Lk;
;   unsigned char* lds_t = smem + tid * 16;
;     ...
;   asm volatile("s_waitcnt vmcnt(0)" ::: "memory");
;   RAW_BARRIER();
;   ATT_ISSUE(0, 0);
;   if (nt > 1) ATT_ISSUE(1, 1);
;   const int sw8 = (l16 >> 1) & 7, vsw = sw8 << 1;
;   const unsigned ka0 = l16 * 128 + ((g ^ sw8) << 4), ka1 = l16 * 128 + (((4 + g) ^ sw8) << 4);
;   const unsigned kr = 8192 + l16 * 64 + ((g ^ ((0 - (l16 >> 2)) & 3)) << 4);
;   const unsigned vb00 = 12288 + l16 * 128 + (((0 + g) ^ vsw) << 3), vb01 = 12288 + l16 * 128 + (((4 + g) ^ vsw) << 3);
;   const unsigned vb10 = 12288 + l16 * 128 + (((8 + g) ^ vsw) << 3), vb11 = 12288 + l16 * 128 + (((12 + g) ^ vsw) << 3);
;   const unsigned biasA = lbase + ATT_BIAS_OFF;
;   const int qc = w * 16 + l16;
;   const int cs0 = min(max(qc - 8, 0), 48);
;   int cs = 0, is = 2;
; DEVI void attn_dense_phase(const Params& p, unsigned char* smem, unsigned* ctr) {
;     ...
;       const int hq = h16 - 8, kvh = hq >> 2;
;       a.Q = Hb + H_PROJ + (size_t)q0 * 1056 + 384 + hq * 64; a.ldq = 1056;
;       a.K = Hb + H_PROJ + (size_t)kb * 1056 + 896 + kvh * 64; a.ldk = 1056;
;       a.Vt = Hb + H_VTG + (size_t)128 * kb + (size_t)(kvh * 64) * Lk;
;       a.sc2 = 0.125f * LOG2E;
;       attn_item<64, 2, false>(a, smem);
.LBB0_2263:
	s_or_b32 s62, s60, 64
	s_lshl_b32 s0, s8, 7
	s_cmp_lt_i32 s8, 0
	s_cselect_b32 s0, s60, s0
	s_add_i32 s59, s2, s0
	s_lshr_b32 s61, s60, 6
	s_lshl_b32 s56, s58, 6
	s_cmp_gt_u32 s58, 7
	s_cbranch_scc0 .LBB0_2289
	s_add_i32 s0, s58, -8
	s_mul_i32 s3, s59, 0x840
	v_readlane_b32 s28, v251, 52
	s_mul_hi_i32 s1, s59, 0x840
	s_add_u32 s3, s28, s3
	v_readlane_b32 s29, v251, 53
	s_addc_u32 s1, s29, s1
	s_lshl_b32 s8, s0, 7
	s_add_u32 s8, s3, s8
	s_addc_u32 s9, s1, 0
	s_ashr_i32 s3, s2, 31
	s_mul_i32 s20, s2, 0x840
	s_mul_hi_i32 s1, s2, 0x840
	s_add_u32 s20, s28, s20
	s_addc_u32 s1, s29, s1
	s_lshl_b32 s0, s0, 4
	s_and_b32 s42, s0, 0x7fffffc0
	s_lshl_b32 s0, s42, 1
	s_add_u32 s40, s20, s0
	s_addc_u32 s41, s1, 0
	s_lshl_b64 s[0:1], s[2:3], 8
	v_readlane_b32 s3, v251, 56
	s_add_u32 s3, s3, s0
	v_readlane_b32 s0, v251, 57
	s_addc_u32 s20, s0, s1
	s_mul_hi_u32 s1, s62, s42
	s_mul_i32 s0, s62, s42
	v_mov_b32_e32 v3, v177
	s_lshl_b64 s[0:1], s[0:1], 1
	s_add_u32 s42, s3, s0
	v_ashrrev_i32_e32 v0, 1, v3
	v_and_b32_e32 v128, 0xffffffe0, v0
	s_addc_u32 s43, s20, s1
	v_cmp_gt_i32_e64 s[0:1], s57, v128
	v_and_b32_e32 v126, 15, v3
	v_bfe_u32 v127, v3, 4, 2
	v_cndmask_b32_e64 v0, 0, v128, s[0:1]
	v_or_b32_e32 v12, v0, v126
	v_lshlrev_b32_e32 v0, 4, v127
	v_lshrrev_b32_e32 v2, 4, v3
	v_lshl_add_u64 v[4:5], s[8:9], 0, v[0:1]
	s_movk_i32 s3, 0x840
	v_or_b32_e32 v0, 16, v12
	v_mad_i64_i32 v[6:7], s[8:9], v12, s3, v[4:5]
	v_mad_i64_i32 v[4:5], s[8:9], v0, s3, v[4:5]
	v_xor_b32_e32 v0, v2, v3
	v_ashrrev_i32_e32 v22, 3, v3
	v_mov_b64_e32 v[20:21], s[40:41]
	v_lshlrev_b32_e32 v0, 4, v0
	v_mad_i64_i32 v[20:21], s[8:9], v22, s3, v[20:21]
	v_and_b32_e32 v0, 0x70, v0
	v_lshl_add_u64 v[106:107], v[20:21], 0, v[0:1]
	s_mov_b64 s[8:9], 0x700
	v_lshl_add_u64 v[20:21], v[106:107], 0, s[8:9]
	v_mad_i64_i32 v[22:23], s[8:9], v22, s62, 0
	v_lshl_add_u64 v[22:23], v[22:23], 1, s[42:43]
	v_lshlrev_b32_e32 v185, 4, v3
	v_lshl_add_u64 v[104:105], v[22:23], 0, v[0:1]
	v_readfirstlane_b32 s3, v185
	v_add_u32_e32 v0, 0x1000, v185
	global_load_dwordx4 v[16:19], v[6:7], off offset:768
	global_load_dwordx4 v[8:11], v[6:7], off offset:832
	global_load_dwordx4 v[12:15], v[4:5], off offset:768
	s_nop 0
	global_load_dwordx4 v[4:7], v[4:5], off offset:832
	s_waitcnt vmcnt(0)
	s_mov_b32 m0, s3
	s_mov_b64 s[8:9], 0x10f00
	v_readfirstlane_b32 s3, v0
	v_add_u32_e32 v0, 0x3000, v185
	s_waitcnt lgkmcnt(0)
	s_barrier
	global_load_lds_dwordx4 v[20:21], off
	v_lshl_add_u64 v[20:21], v[106:107], 0, s[8:9]
	s_mov_b32 m0, s3
	v_readfirstlane_b32 s3, v0
	v_add_u32_e32 v0, 0x4000, v185
	global_load_lds_dwordx4 v[20:21], off
	s_mov_b32 m0, s3
	s_lshl_b32 s20, s62, 6
	v_readfirstlane_b32 s3, v0
	v_add_u32_e32 v0, 0x5000, v185
	global_load_lds_dwordx4 v[104:105], off
	v_lshl_add_u64 v[108:109], v[104:105], 0, s[20:21]
	s_mov_b32 m0, s3
	s_mov_b64 s[8:9], 0x21700
	v_readfirstlane_b32 s3, v0
	v_add_u32_e32 v0, 0x6000, v185
	global_load_lds_dwordx4 v[108:109], off
	v_lshl_add_u64 v[20:21], v[106:107], 0, s[8:9]
	s_mov_b32 m0, s3
	s_mov_b64 s[8:9], 0x31f00
	v_readfirstlane_b32 s3, v0
	v_add_u32_e32 v0, 0x8000, v185
	global_load_lds_dwordx4 v[20:21], off
	v_lshl_add_u64 v[20:21], v[106:107], 0, s[8:9]
	s_mov_b32 m0, s3
	s_mov_b64 s[8:9], 0x80
	v_readfirstlane_b32 s3, v0
	v_add_u32_e32 v0, 0x9000, v185
	global_load_lds_dwordx4 v[20:21], off
	v_lshl_add_u64 v[20:21], v[104:105], 0, s[8:9]
	s_mov_b32 m0, s3
	v_readfirstlane_b32 s3, v0
	global_load_lds_dwordx4 v[20:21], off
	v_lshl_add_u64 v[20:21], v[108:109], 0, s[8:9]
	s_mov_b32 m0, s3
	v_add_u32_e32 v0, 0xa000, v185
	global_load_lds_dwordx4 v[20:21], off
	s_mov_b64 s[8:9], 0x42700
	v_readfirstlane_b32 s3, v0
	v_add_u32_e32 v0, 0xb000, v185
	s_waitcnt vmcnt(4)
	v_lshl_add_u64 v[20:21], v[106:107], 0, s[8:9]
	s_mov_b32 m0, s3
	s_mov_b64 s[8:9], 0x52f00
	v_readfirstlane_b32 s3, v0
	v_add_u32_e32 v0, 0xd000, v185
	s_waitcnt lgkmcnt(0)
	s_barrier
	global_load_lds_dwordx4 v[20:21], off
	v_lshl_add_u64 v[20:21], v[106:107], 0, s[8:9]
	s_mov_b32 m0, s3
	s_mov_b64 s[8:9], 0x100
	v_readfirstlane_b32 s3, v0
	v_add_u32_e32 v0, 0xe000, v185
	global_load_lds_dwordx4 v[20:21], off
	v_lshl_add_u64 v[20:21], v[104:105], 0, s[8:9]
	s_mov_b32 m0, s3
	v_readfirstlane_b32 s3, v0
	global_load_lds_dwordx4 v[20:21], off
	v_lshl_add_u64 v[20:21], v[108:109], 0, s[8:9]
	s_mov_b32 m0, s3
	v_cmp_le_i32_e32 vcc, s57, v128
	global_load_lds_dwordx4 v[20:21], off
	s_and_saveexec_b64 s[8:9], vcc
	s_xor_b64 s[8:9], exec, s[8:9]
	s_or_saveexec_b64 s[42:43], s[8:9]
	v_bfe_u32 v0, v3, 1, 3
	v_lshlrev_b32_e32 v3, 1, v0
	v_lshlrev_b32_e32 v20, 7, v126
	v_bitop3_b32 v21, v2, v0, 3 bitop3:0x6c
	v_bitop3_b32 v0, v127, v0, 4 bitop3:0x36
	v_lshl_or_b32 v184, v0, 4, v20
	v_or_b32_e32 v0, 0x3000, v20
	v_bitop3_b32 v2, v3, v2, 3 bitop3:0x78
	v_lshl_or_b32 v129, v2, 3, v0
	v_bitop3_b32 v2, v127, v3, 4 bitop3:0x36
	v_lshl_or_b32 v180, v2, 3, v0
	v_bitop3_b32 v2, v127, v3, 8 bitop3:0x36
	v_lshl_or_b32 v181, v2, 3, v0
	v_bitop3_b32 v2, v127, v3, 12 bitop3:0x36
	v_lshl_or_b32 v182, v2, 3, v0
	v_mov_b32_e32 v2, v1
	v_mov_b32_e32 v3, v1
	v_lshl_or_b32 v183, v21, 4, v20
	v_mov_b32_e32 v0, v1
	v_mov_b64_e32 v[22:23], v[2:3]
	v_mov_b64_e32 v[26:27], v[2:3]
	v_mov_b64_e32 v[30:31], v[2:3]
	v_mov_b64_e32 v[34:35], v[2:3]
	v_mov_b64_e32 v[38:39], v[2:3]
	v_mov_b64_e32 v[42:43], v[2:3]
	v_mov_b64_e32 v[46:47], v[2:3]
	v_mov_b64_e32 v[50:51], v[2:3]
	s_mov_b32 s8, 0
	v_mov_b32_e32 v100, 0
	v_mov_b64_e32 v[20:21], v[0:1]
	v_mov_b64_e32 v[24:25], v[0:1]
	v_mov_b64_e32 v[28:29], v[0:1]
	v_mov_b64_e32 v[32:33], v[0:1]
	v_mov_b64_e32 v[36:37], v[0:1]
	v_mov_b64_e32 v[40:41], v[0:1]
	v_mov_b64_e32 v[44:45], v[0:1]
	v_mov_b64_e32 v[48:49], v[0:1]
	v_mov_b32_e32 v101, 0
	v_mov_b32_e32 v102, 0
	v_mov_b32_e32 v103, 0
	s_xor_b64 exec, exec, s[42:43]
	s_cbranch_execz .LBB0_2266
; template <int DK, int QB, bool NA>
; DEVI void attn_item(const AttnArgs& a, unsigned char* smem) {
;     ...
;         const unsigned a0 = cur + ka0, a1 = cur + ka1, a2 = cur + kr;
;         k0[0] = ldsr<0>(a0); k0[1] = ldsr<2048>(a0); k0[2] = ldsr<4096>(a0); k0[3] = ldsr<6144>(a0);
;         k1[0] = ldsr<0>(a1); k1[1] = ldsr<2048>(a1); k1[2] = ldsr<4096>(a1); k1[3] = ldsr<6144>(a1);
;         if constexpr (KS == 3) { k2[0] = ldsr<0>(a2); k2[1] = ldsr<1024>(a2); k2[2] = ldsr<2048>(a2); k2[3] = ldsr<3072>(a2); }
;         if constexpr (KS == 3) asm volatile("s_waitcnt lgkmcnt(8)" : "+v"(k0[0]), "+v"(k0[1]), "+v"(k0[2]), "+v"(k0[3]) :: "memory");
;         else                   asm volatile("s_waitcnt lgkmcnt(4)" : "+v"(k0[0]), "+v"(k0[1]), "+v"(k0[2]), "+v"(k0[3]) :: "memory");
;         __builtin_amdgcn_sched_barrier(0);
; #pragma unroll
;         for (int kb = 0; kb < 4; ++kb)
; #pragma unroll
;           for (int qb = 0; qb < QB; ++qb) s[kb][qb] = __builtin_amdgcn_mfma_f32_16x16x32_bf16(k0[kb], qf[qb][0], s[kb][qb], 0, 0, 0);
;         if constexpr (KS == 3) asm volatile("s_waitcnt lgkmcnt(4)" : "+v"(k1[0]), "+v"(k1[1]), "+v"(k1[2]), "+v"(k1[3]) :: "memory");
;         else                   asm volatile("s_waitcnt lgkmcnt(0)" : "+v"(k1[0]), "+v"(k1[1]), "+v"(k1[2]), "+v"(k1[3]) :: "memory");
;         __builtin_amdgcn_sched_barrier(0);
; #pragma unroll
;         for (int kb = 0; kb < 4; ++kb)
; #pragma unroll
;           for (int qb = 0; qb < QB; ++qb) s[kb][qb] = __builtin_amdgcn_mfma_f32_16x16x32_bf16(k1[kb], qf[qb][1], s[kb][qb], 0, 0, 0);
;     ...
;           const f32x2 scv = {a.sc2, a.sc2}, nmv = {-m[qb], -m[qb]};
;           f32x2 t[4][2];
; #pragma unroll
;           for (int kb = 0; kb < 4; ++kb)
; #pragma unroll
;             for (int h = 0; h < 2; ++h) {
;               const f32x2 sv = {s[kb][qb][2 * h], s[kb][qb][2 * h + 1]};
;               t[kb][h] = sv * scv + nmv;
;             }
;           float mx = fmaxf(t[0][0].x, t[0][0].y);
; #pragma unroll
;           for (int kb = 0; kb < 4; ++kb)
; #pragma unroll
;             for (int h = 0; h < 2; ++h) mx = fmaxf(mx, fmaxf(t[kb][h].x, t[kb][h].y));
;           if (j == 0 || __any(mx > 6.f)) {
;             mx = xmax32(xmax16(mx));
;             const float d = (j == 0) ? mx : fmaxf(mx, 0.f);
;             const float alpha = __builtin_amdgcn_exp2f(-d);
;             const f32x2 dv = {d, d};
; #pragma unroll
	ds_read_b128 v[20:23], v183 offset:0
	ds_read_b128 v[24:27], v183 offset:0x800
	ds_read_b128 v[28:31], v183 offset:0x1000
	ds_read_b128 v[32:35], v183 offset:0x1800
	ds_read_b128 v[36:39], v184 offset:0
	ds_read_b128 v[40:43], v184 offset:0x800
	ds_read_b128 v[44:47], v184 offset:0x1000
	ds_read_b128 v[48:51], v184 offset:0x1800
	s_nop 0
	s_waitcnt lgkmcnt(4)
	s_waitcnt vmcnt(0)
	s_setprio 1
	v_mfma_f32_16x16x32_bf16 v[52:55], v[20:23], v[16:19], 0
	s_waitcnt lgkmcnt(0)
	v_mfma_f32_16x16x32_bf16 v[20:23], v[20:23], v[12:15], 0
	v_mfma_f32_16x16x32_bf16 v[56:59], v[24:27], v[16:19], 0
	v_mfma_f32_16x16x32_bf16 v[24:27], v[24:27], v[12:15], 0
	v_mfma_f32_16x16x32_bf16 v[68:71], v[28:31], v[16:19], 0
	v_mfma_f32_16x16x32_bf16 v[28:31], v[28:31], v[12:15], 0
	v_mfma_f32_16x16x32_bf16 v[72:75], v[32:35], v[16:19], 0
	v_mfma_f32_16x16x32_bf16 v[32:35], v[32:35], v[12:15], 0
	v_mfma_f32_16x16x32_bf16 v[52:55], v[36:39], v[8:11], v[52:55]
	v_mfma_f32_16x16x32_bf16 v[56:59], v[40:43], v[8:11], v[56:59]
	v_mfma_f32_16x16x32_bf16 v[76:79], v[44:47], v[8:11], v[68:71]
	s_nop 5
	v_mul_f32_e64 v84, v54, s92
	v_mul_f32_e64 v85, v55, s92
	v_pk_mul_f32 v[2:3], v[52:53], s[92:93] op_sel_hi:[1,0]
	v_max_f32_e32 v0, v84, v85
	v_max3_f32 v0, v2, v3, v0
	v_pk_mul_f32 v[2:3], v[56:57], s[92:93] op_sel_hi:[1,0]
	v_mfma_f32_16x16x32_bf16 v[80:83], v[48:51], v[8:11], v[72:75]
	v_max_f32_e32 v84, v2, v3
	v_pk_mul_f32 v[2:3], v[58:59], s[92:93] op_sel_hi:[1,0]
	s_nop 0
	v_max_f32_e32 v2, v2, v3
	v_max3_f32 v0, v0, v84, v2
	v_pk_mul_f32 v[2:3], v[76:77], s[92:93] op_sel_hi:[1,0]
	v_mfma_f32_16x16x32_bf16 v[60:63], v[36:39], v[4:7], v[20:23]
	v_max_f32_e32 v84, v2, v3
	v_pk_mul_f32 v[2:3], v[78:79], s[92:93] op_sel_hi:[1,0]
	s_nop 0
	v_max_f32_e32 v2, v2, v3
	v_max3_f32 v0, v0, v84, v2
	v_pk_mul_f32 v[2:3], v[80:81], s[92:93] op_sel_hi:[1,0]
	v_mfma_f32_16x16x32_bf16 v[64:67], v[40:43], v[4:7], v[24:27]
	s_setprio 0
	v_max_f32_e32 v84, v2, v3
	v_pk_mul_f32 v[2:3], v[82:83], s[92:93] op_sel_hi:[1,0]
	s_nop 0
	v_max_f32_e32 v2, v2, v3
	v_max3_f32 v0, v0, v84, v2
	v_mov_b32_e32 v2, v0
	s_nop 1
	v_permlane16_swap_b32_e32 v0, v2
	v_max_f32_e32 v2, v2, v2
	v_max_f32_e32 v0, v0, v0
	v_max_f32_e32 v0, v0, v2
	v_mov_b32_e32 v2, v0
	s_nop 1
	v_permlane32_swap_b32_e32 v0, v2
	v_max_f32_e32 v2, v2, v2
	v_max_f32_e32 v0, v0, v0
	v_max_f32_e32 v84, v0, v2
	v_fma_f32 v52, v52, s92, -v84
	v_fma_f32 v53, v53, s92, -v84
	v_fma_f32 v54, v54, s92, -v84
	v_fma_f32 v55, v55, s92, -v84
	v_exp_f32_e32 v52, v52
	v_exp_f32_e32 v53, v53
	v_exp_f32_e32 v54, v54
	v_exp_f32_e32 v55, v55
	v_fma_f32 v56, v56, s92, -v84
	v_fma_f32 v57, v57, s92, -v84
	v_pk_add_f32 v[86:87], v[52:53], 0 op_sel_hi:[1,0]
	v_fma_f32 v58, v58, s92, -v84
	v_fma_f32 v59, v59, s92, -v84
	v_cvt_pk_bf16_f32 v52, v52, v53
	v_pk_add_f32 v[86:87], v[54:55], v[86:87]
	v_cvt_pk_bf16_f32 v53, v54, v55
	v_exp_f32_e32 v54, v56
	v_exp_f32_e32 v55, v57
	v_exp_f32_e32 v58, v58
	v_exp_f32_e32 v59, v59
	v_fma_f32 v76, v76, s92, -v84
	v_fma_f32 v77, v77, s92, -v84
	v_pk_add_f32 v[56:57], v[54:55], v[86:87]
	v_cvt_pk_bf16_f32 v54, v54, v55
	v_pk_add_f32 v[56:57], v[58:59], v[56:57]
	v_cvt_pk_bf16_f32 v55, v58, v59
	v_exp_f32_e32 v58, v76
	v_exp_f32_e32 v59, v77
	v_fma_f32 v78, v78, s92, -v84
	v_fma_f32 v79, v79, s92, -v84
	v_fma_f32 v80, v80, s92, -v84
	v_fma_f32 v81, v81, s92, -v84
	v_fma_f32 v82, v82, s92, -v84
	v_fma_f32 v83, v83, s92, -v84
	v_pk_add_f32 v[76:77], v[58:59], v[56:57]
	v_cvt_pk_bf16_f32 v56, v58, v59
	v_exp_f32_e32 v58, v78
	v_exp_f32_e32 v59, v79
	v_exp_f32_e32 v78, v82
	v_exp_f32_e32 v79, v83
	s_setprio 1
	v_mfma_f32_16x16x32_bf16 v[68:71], v[44:47], v[4:7], v[28:31]
	v_add_f32_e64 v76, v58, v76
	v_add_f32_e64 v77, v59, v77
	v_cvt_pk_bf16_f32 v57, v58, v59
	v_exp_f32_e32 v58, v80
	v_exp_f32_e32 v59, v81
	v_pk_mul_f32 v[80:81], v[62:63], s[92:93] op_sel_hi:[1,0]
	v_mfma_f32_16x16x32_bf16 v[72:75], v[48:51], v[4:7], v[32:35]
	s_setprio 0
	v_max_f32_e32 v0, v80, v81
	v_pk_add_f32 v[76:77], v[58:59], v[76:77]
	v_cvt_pk_bf16_f32 v58, v58, v59
	v_pk_add_f32 v[76:77], v[78:79], v[76:77]
	v_cvt_pk_bf16_f32 v59, v78, v79
	v_pk_mul_f32 v[78:79], v[60:61], s[92:93] op_sel_hi:[1,0]
	v_exp_f32_e64 v3, -v84
	v_max3_f32 v0, v78, v79, v0
	v_pk_mul_f32 v[78:79], v[64:65], s[92:93] op_sel_hi:[1,0]
	ds_read_b64 v[48:49], v129 offset:0
	ds_read_b64 v[50:51], v180 offset:0
	ds_read_b64 v[44:45], v129 offset:0x800
	ds_read_b64 v[46:47], v180 offset:0x800
	ds_read_b64 v[40:41], v129 offset:0x1000
	s_nop 0
	v_max_f32_e32 v2, v78, v79
	v_pk_mul_f32 v[78:79], v[66:67], s[92:93] op_sel_hi:[1,0]
	ds_read_b64 v[42:43], v180 offset:0x1000
	ds_read_b64 v[36:37], v129 offset:0x1800
	ds_read_b64 v[38:39], v180 offset:0x1800
	ds_read_b64 v[32:33], v181 offset:0
	ds_read_b64 v[34:35], v182 offset:0
	s_nop 0
	v_max_f32_e32 v78, v78, v79
	v_max3_f32 v0, v0, v2, v78
	v_pk_mul_f32 v[78:79], v[68:69], s[92:93] op_sel_hi:[1,0]
	ds_read_b64 v[28:29], v181 offset:0x800
	ds_read_b64 v[30:31], v182 offset:0x800
	ds_read_b64 v[24:25], v181 offset:0x1000
	ds_read_b64 v[26:27], v182 offset:0x1000
	ds_read_b64 v[20:21], v181 offset:0x1800
	s_nop 0
	v_max_f32_e32 v2, v78, v79
	v_pk_mul_f32 v[78:79], v[70:71], s[92:93] op_sel_hi:[1,0]
	ds_read_b64 v[22:23], v182 offset:0x1800
	s_nop 0
	v_max_f32_e32 v78, v78, v79
	v_max3_f32 v0, v0, v2, v78
	v_pk_mul_f32 v[78:79], v[72:73], s[92:93] op_sel_hi:[1,0]
	s_waitcnt lgkmcnt(0)
; template <int DK, int QB, bool NA>
; DEVI void attn_item(const AttnArgs& a, unsigned char* smem) {
;     ...
;           const f32x2 scv = {a.sc2, a.sc2}, nmv = {-m[qb], -m[qb]};
;           f32x2 t[4][2];
; #pragma unroll
;           for (int kb = 0; kb < 4; ++kb)
; #pragma unroll
;             for (int h = 0; h < 2; ++h) {
;               const f32x2 sv = {s[kb][qb][2 * h], s[kb][qb][2 * h + 1]};
;               t[kb][h] = sv * scv + nmv;
;             }
;           float mx = fmaxf(t[0][0].x, t[0][0].y);
; #pragma unroll
;           for (int kb = 0; kb < 4; ++kb)
; #pragma unroll
;             for (int h = 0; h < 2; ++h) mx = fmaxf(mx, fmaxf(t[kb][h].x, t[kb][h].y));
;           if (j == 0 || __any(mx > 6.f)) {
;             mx = xmax32(xmax16(mx));
;             const float d = (j == 0) ? mx : fmaxf(mx, 0.f);
;             const float alpha = __builtin_amdgcn_exp2f(-d);
;             const f32x2 dv = {d, d};
; #pragma unroll
;             for (int kb = 0; kb < 4; ++kb)
; #pragma unroll
;               for (int h = 0; h < 2; ++h) t[kb][h] -= dv;
;             m[qb] += d;
;             l[qb] *= alpha;
; #pragma unroll
;             for (int db = 0; db < 4; ++db) o[db][qb] *= alpha;
;           }
;           f32x2 ls2 = {0.f, 0.f};
;           unsigned pw[2][4];
; #pragma unroll
;           for (int kb = 0; kb < 4; ++kb)
; #pragma unroll
;             for (int h = 0; h < 2; ++h) {
;               const f32x2 pe = {__builtin_amdgcn_exp2f(t[kb][h].x), __builtin_amdgcn_exp2f(t[kb][h].y)};
;               ls2 += pe;
;               pw[kb >> 1][(kb & 1) * 2 + h] = pk2(pe.x, pe.y);
;             }
;           l[qb] += ls2.x + ls2.y;
; #pragma unroll
;           for (int c = 0; c < 2; ++c) {
;             const u32x4 pv = (u32x4){pw[c][0], pw[c][1], pw[c][2], pw[c][3]};
;             pf[qb][c] = __builtin_bit_cast(bf16x8, pv);
;           }
;         }
;     ...
;       asm volatile("s_waitcnt lgkmcnt(0)"
;                    : "+v"(va[0][0]), "+v"(va[0][1]), "+v"(va[0][2]), "+v"(va[0][3]), "+v"(va[1][0]), "+v"(va[1][1]), "+v"(va[1][2]), "+v"(va[1][3]),
;                      "+v"(vbq[0][0]), "+v"(vbq[0][1]), "+v"(vbq[0][2]), "+v"(vbq[0][3]), "+v"(vbq[1][0]), "+v"(vbq[1][1]), "+v"(vbq[1][2]), "+v"(vbq[1][3])
;                    :: "memory");
;       __builtin_amdgcn_sched_barrier(0);
; #pragma unroll
;       for (int c = 0; c < 2; ++c)
; #pragma unroll
	s_nop 0
	v_max_f32_e32 v2, v78, v79
	v_pk_mul_f32 v[78:79], v[74:75], s[92:93] op_sel_hi:[1,0]
	s_nop 0
	v_max_f32_e32 v78, v78, v79
	v_max3_f32 v0, v0, v2, v78
	v_mov_b32_e32 v2, v0
	s_nop 1
	v_permlane16_swap_b32_e32 v0, v2
	v_max_f32_e32 v2, v2, v2
	v_max_f32_e32 v0, v0, v0
	v_max_f32_e32 v0, v0, v2
	v_mov_b32_e32 v2, v0
	s_nop 1
	v_permlane32_swap_b32_e32 v0, v2
	v_max_f32_e32 v2, v2, v2
	v_max_f32_e32 v0, v0, v0
	v_max_f32_e32 v85, v0, v2
	v_mov_b32_e32 v0, v85
	v_fma_f32 v60, v60, s92, -v0
	v_fma_f32 v61, v61, s92, -v0
	v_fma_f32 v62, v62, s92, -v0
	v_fma_f32 v63, v63, s92, -v0
	v_exp_f32_e32 v60, v60
	v_exp_f32_e32 v61, v61
	v_exp_f32_e32 v62, v62
	v_exp_f32_e32 v63, v63
	v_fma_f32 v64, v64, s92, -v0
	v_fma_f32 v65, v65, s92, -v0
	v_pk_add_f32 v[78:79], v[60:61], 0 op_sel_hi:[1,0]
	v_fma_f32 v66, v66, s92, -v0
	v_fma_f32 v67, v67, s92, -v0
	v_cvt_pk_bf16_f32 v60, v60, v61
	v_pk_add_f32 v[78:79], v[62:63], v[78:79]
	v_cvt_pk_bf16_f32 v61, v62, v63
	v_exp_f32_e32 v62, v64
	v_exp_f32_e32 v63, v65
	v_exp_f32_e32 v66, v66
	v_exp_f32_e32 v67, v67
	v_fma_f32 v68, v68, s92, -v0
	v_fma_f32 v69, v69, s92, -v0
	v_pk_add_f32 v[64:65], v[62:63], v[78:79]
	v_cvt_pk_bf16_f32 v62, v62, v63
	v_pk_add_f32 v[64:65], v[66:67], v[64:65]
	v_cvt_pk_bf16_f32 v63, v66, v67
	v_exp_f32_e32 v66, v68
	v_exp_f32_e32 v67, v69
	v_fma_f32 v70, v70, s92, -v0
	v_fma_f32 v71, v71, s92, -v0
	v_fma_f32 v72, v72, s92, -v0
	v_fma_f32 v73, v73, s92, -v0
	v_fma_f32 v74, v74, s92, -v0
	v_fma_f32 v75, v75, s92, -v0
	v_pk_add_f32 v[68:69], v[66:67], v[64:65]
	v_cvt_pk_bf16_f32 v64, v66, v67
	v_exp_f32_e32 v66, v70
	v_exp_f32_e32 v67, v71
	v_exp_f32_e32 v70, v74
	v_exp_f32_e32 v71, v75
	v_exp_f32_e64 v2, -v85
	v_pk_add_f32 v[68:69], v[66:67], v[68:69]
	v_cvt_pk_bf16_f32 v65, v66, v67
	v_exp_f32_e32 v66, v72
	v_exp_f32_e32 v67, v73
	v_pk_add_f32 v[102:103], v[84:85], 0 op_sel_hi:[1,0]
	v_pk_add_f32 v[68:69], v[66:67], v[68:69]
	s_nop 0
	v_pk_add_f32 v[78:79], v[70:71], v[68:69]
	v_cvt_pk_bf16_f32 v66, v66, v67
	v_cvt_pk_bf16_f32 v67, v70, v71
	v_mov_b32_e32 v70, v78
	v_mov_b32_e32 v71, v76
	v_mov_b32_e32 v76, v79
	v_pk_add_f32 v[76:77], v[70:71], v[76:77]
	v_pk_mul_f32 v[68:69], v[2:3], 0 op_sel_hi:[1,0]
	v_pk_fma_f32 v[100:101], v[2:3], 0, v[76:77] op_sel_hi:[1,0,1]
	v_mov_b32_e32 v72, v69
	v_mov_b32_e32 v73, v69
	v_mov_b32_e32 v74, v69
	v_mov_b32_e32 v75, v69
	v_mov_b32_e32 v69, v68
	v_mov_b32_e32 v70, v68
	v_mov_b32_e32 v71, v68
	s_setprio 1
	v_mfma_f32_16x16x32_bf16 v[76:79], v[48:51], v[52:55], v[72:75]
	s_nop 0
	v_mfma_f32_16x16x32_bf16 v[80:83], v[48:51], v[60:63], v[68:71]
	v_mfma_f32_16x16x32_bf16 v[84:87], v[44:47], v[52:55], v[72:75]
	v_mfma_f32_16x16x32_bf16 v[88:91], v[44:47], v[60:63], v[68:71]
	v_mfma_f32_16x16x32_bf16 v[92:95], v[40:43], v[52:55], v[72:75]
	v_mfma_f32_16x16x32_bf16 v[96:99], v[40:43], v[60:63], v[68:71]
	v_mfma_f32_16x16x32_bf16 v[52:55], v[36:39], v[52:55], v[72:75]
	v_mfma_f32_16x16x32_bf16 v[60:63], v[36:39], v[60:63], v[68:71]
	v_mfma_f32_16x16x32_bf16 v[48:51], v[32:35], v[56:59], v[76:79]
	v_mfma_f32_16x16x32_bf16 v[44:47], v[32:35], v[64:67], v[80:83]
	v_mfma_f32_16x16x32_bf16 v[40:43], v[28:31], v[56:59], v[84:87]
	v_mfma_f32_16x16x32_bf16 v[36:39], v[28:31], v[64:67], v[88:91]
	v_mfma_f32_16x16x32_bf16 v[32:35], v[24:27], v[56:59], v[92:95]
	v_mfma_f32_16x16x32_bf16 v[28:31], v[24:27], v[64:67], v[96:99]
	v_mfma_f32_16x16x32_bf16 v[24:27], v[20:23], v[56:59], v[52:55]
	v_mfma_f32_16x16x32_bf16 v[20:23], v[20:23], v[64:67], v[60:63]
	s_setprio 0

; template <int DK, int QB, bool NA>
; DEVI void attn_item(const AttnArgs& a, unsigned char* smem) {
;     ...
;   for (int j = 0; j < nt; ++j) {
;     if (j + 1 < nt) {
;       if constexpr (DK == 96) asm volatile("s_waitcnt vmcnt(5)" ::: "memory");
;       else                    asm volatile("s_waitcnt vmcnt(4)" ::: "memory");
;     } else {
;       asm volatile("s_waitcnt vmcnt(0)" ::: "memory");
;     }
;     RAW_BARRIER();
;     if (j + 2 < nt) ATT_ISSUE(j + 2, is);
;     is = (is + 1 == S) ? 0 : is + 1;
;     const unsigned cur = lbase + cs * ATT_STAGE;
;     cs = (cs + 1 == S) ? 0 : cs + 1;
;     if (wact) {
;       f32x4 s[4][QB];
; #pragma unroll
;       for (int kb = 0; kb < 4; ++kb)
; #pragma unroll
;         for (int qb = 0; qb < QB; ++qb) s[kb][qb] = (f32x4){0.f, 0.f, 0.f, 0.f};
;       {
;         bf16x8 k0[4], k1[4], k2[4];
;         const unsigned a0 = cur + ka0, a1 = cur + ka1, a2 = cur + kr;
;         k0[0] = ldsr<0>(a0); k0[1] = ldsr<2048>(a0); k0[2] = ldsr<4096>(a0); k0[3] = ldsr<6144>(a0);
;         k1[0] = ldsr<0>(a1); k1[1] = ldsr<2048>(a1); k1[2] = ldsr<4096>(a1); k1[3] = ldsr<6144>(a1);
;         if constexpr (KS == 3) { k2[0] = ldsr<0>(a2); k2[1] = ldsr<1024>(a2); k2[2] = ldsr<2048>(a2); k2[3] = ldsr<3072>(a2); }
;         if constexpr (KS == 3) asm volatile("s_waitcnt lgkmcnt(8)" : "+v"(k0[0]), "+v"(k0[1]), "+v"(k0[2]), "+v"(k0[3]) :: "memory");
;         else                   asm volatile("s_waitcnt lgkmcnt(4)" : "+v"(k0[0]), "+v"(k0[1]), "+v"(k0[2]), "+v"(k0[3]) :: "memory");
;         __builtin_amdgcn_sched_barrier(0);
; #pragma unroll
;         for (int kb = 0; kb < 4; ++kb)
; #pragma unroll
;           for (int qb = 0; qb < QB; ++qb) s[kb][qb] = __builtin_amdgcn_mfma_f32_16x16x32_bf16(k0[kb], qf[qb][0], s[kb][qb], 0, 0, 0);
;         if constexpr (KS == 3) asm volatile("s_waitcnt lgkmcnt(4)" : "+v"(k1[0]), "+v"(k1[1]), "+v"(k1[2]), "+v"(k1[3]) :: "memory");
;         else                   asm volatile("s_waitcnt lgkmcnt(0)" : "+v"(k1[0]), "+v"(k1[1]), "+v"(k1[2]), "+v"(k1[3]) :: "memory");
;         __builtin_amdgcn_sched_barrier(0);
; #pragma unroll
;         for (int kb = 0; kb < 4; ++kb)
; #pragma unroll
;           for (int qb = 0; qb < QB; ++qb) s[kb][qb] = __builtin_amdgcn_mfma_f32_16x16x32_bf16(k1[kb], qf[qb][1], s[kb][qb], 0, 0, 0);
;         if constexpr (KS == 3) {
.LBB0_2269:
	s_add_i32 s9, s9, 1
	s_cmp_lt_u32 s9, s61
	s_cselect_b32 s20, s44, s60
	s_mul_i32 s40, s8, 0x5000
	v_add_u32_e32 v0, s40, v185
	v_mad_u64_u32 v[2:3], s[40:41], s20, v205, v[106:107]
	s_mov_b64 s[28:29], 0x700
	v_readfirstlane_b32 s40, v0
	s_mul_i32 s100, s3, 0x5000
	v_or_b32_e32 v208, s100, v183
	v_or_b32_e32 v209, s100, v184
	s_waitcnt vmcnt(4)
	v_lshl_add_u64 v[210:211], v[2:3], 0, s[28:29]
	s_mov_b32 m0, s40
	s_waitcnt lgkmcnt(0)
	s_barrier
	ds_read_b128 v[52:55], v208 offset:0
	ds_read_b128 v[56:59], v208 offset:0x800
	ds_read_b128 v[60:63], v208 offset:0x1000
	ds_read_b128 v[64:67], v208 offset:0x1800
	ds_read_b128 v[68:71], v209 offset:0
	ds_read_b128 v[72:75], v209 offset:0x800
	ds_read_b128 v[76:79], v209 offset:0x1000
	ds_read_b128 v[80:83], v209 offset:0x1800
	s_and_saveexec_b64 s[42:43], s[0:1]
	s_cbranch_execz .Lgq_dma_stub
	s_waitcnt lgkmcnt(4)
	s_setprio 1
	v_mfma_f32_16x16x32_bf16 v[84:87], v[52:55], v[16:19], 0
	global_load_lds_dwordx4 v[210:211], off
	v_add_u32_e32 v210, 0x1000, v0
	s_waitcnt lgkmcnt(0)
	v_mfma_f32_16x16x32_bf16 v[52:55], v[52:55], v[12:15], 0
	s_mov_b64 s[28:29], 0x10f00
	v_readfirstlane_b32 s40, v210
	v_add_u32_e32 v210, 0x3000, v0
	v_mfma_f32_16x16x32_bf16 v[88:91], v[56:59], v[16:19], 0
	v_lshl_add_u64 v[2:3], v[2:3], 0, s[28:29]
	s_mov_b32 m0, s40
	s_lshl_b64 s[40:41], s[20:21], 1
	v_mfma_f32_16x16x32_bf16 v[56:59], v[56:59], v[12:15], 0
	v_readfirstlane_b32 s20, v210
	v_add_u32_e32 v0, 0x4000, v0
	global_load_lds_dwordx4 v[2:3], off
	v_mfma_f32_16x16x32_bf16 v[110:113], v[60:63], v[16:19], 0
	v_lshl_add_u64 v[2:3], v[104:105], 0, s[40:41]
	s_mov_b32 m0, s20
	v_readfirstlane_b32 s20, v0
	v_mfma_f32_16x16x32_bf16 v[60:63], v[60:63], v[12:15], 0
	global_load_lds_dwordx4 v[2:3], off
	v_lshl_add_u64 v[2:3], v[108:109], 0, s[40:41]
	s_mov_b32 m0, s20
	v_mfma_f32_16x16x32_bf16 v[114:117], v[64:67], v[16:19], 0
	global_load_lds_dwordx4 v[2:3], off
	v_mfma_f32_16x16x32_bf16 v[64:67], v[64:67], v[12:15], 0
	v_mfma_f32_16x16x32_bf16 v[118:121], v[68:71], v[8:11], v[84:87]
	v_add_u32_e32 v0, s100, v129
	v_add_u32_e32 v2, s100, v180
	v_add_u32_e32 v3, s100, v181
	v_mfma_f32_16x16x32_bf16 v[208:211], v[72:75], v[8:11], v[88:91]
	v_mfma_f32_16x16x32_bf16 v[110:113], v[76:79], v[8:11], v[110:113]
	s_nop 2
	v_fma_f32 v120, v120, s92, -v102
	v_fma_f32 v121, v121, s92, -v102
	v_fma_f32 v122, v118, s92, -v102
	v_fma_f32 v123, v119, s92, -v102
	s_nop 0
	v_fma_f32 v118, v210, s92, -v102
	v_fma_f32 v119, v211, s92, -v102
	v_mfma_f32_16x16x32_bf16 v[212:215], v[80:83], v[8:11], v[114:117]
	v_max_f32_e32 v125, v118, v119
	v_fma_f32 v112, v112, s92, -v102
	v_fma_f32 v113, v113, s92, -v102
	v_mfma_f32_16x16x32_bf16 v[96:99], v[68:71], v[4:7], v[52:55]
	v_fma_f32 v116, v208, s92, -v102
	v_fma_f32 v117, v209, s92, -v102
	v_fma_f32 v114, v110, s92, -v102
	v_fma_f32 v115, v111, s92, -v102
	v_max_f32_e32 v124, v116, v117
	v_mfma_f32_16x16x32_bf16 v[92:95], v[72:75], v[4:7], v[56:59]
	v_add_u32_e32 v54, s100, v182
	v_fma_f32 v110, v212, s92, -v102
	v_fma_f32 v111, v213, s92, -v102
	s_mov_b32 s20, 0x40c00000
	v_mfma_f32_16x16x32_bf16 v[88:91], v[76:79], v[4:7], v[60:63]
	v_mfma_f32_16x16x32_bf16 v[84:87], v[80:83], v[4:7], v[64:67]
	s_setprio 0
	ds_read_b64 v[80:81], v0 offset:0
	ds_read_b64 v[82:83], v2 offset:0
	ds_read_b64 v[76:77], v0 offset:0x800
	ds_read_b64 v[78:79], v2 offset:0x800
	ds_read_b64 v[72:73], v0 offset:0x1000
	ds_read_b64 v[74:75], v2 offset:0x1000
	ds_read_b64 v[68:69], v0 offset:0x1800
	v_max_f32_e32 v0, v120, v121
	v_max3_f32 v0, v122, v123, v0
	ds_read_b64 v[70:71], v2 offset:0x1800
	ds_read_b64 v[64:65], v3 offset:0
	ds_read_b64 v[66:67], v54 offset:0
	ds_read_b64 v[60:61], v3 offset:0x800
	ds_read_b64 v[62:63], v54 offset:0x800
	ds_read_b64 v[56:57], v3 offset:0x1000
	ds_read_b64 v[58:59], v54 offset:0x1000
	ds_read_b64 v[52:53], v3 offset:0x1800
	v_fma_f32 v2, v214, s92, -v102
	v_fma_f32 v3, v215, s92, -v102
	v_max3_f32 v0, v0, v124, v125
	v_max_f32_e32 v124, v114, v115
	v_max_f32_e32 v125, v112, v113
	v_max3_f32 v0, v0, v124, v125
	v_max_f32_e32 v124, v110, v111
	v_max_f32_e32 v125, v2, v3
	v_max3_f32 v0, v0, v124, v125
	v_cmp_lt_f32_e32 vcc, s20, v0
	ds_read_b64 v[54:55], v54 offset:0x1800
	s_cbranch_vccz .LBB0_2272
	v_mov_b32_e32 v124, v0
	s_nop 1
	v_permlane16_swap_b32_e32 v0, v124
	v_max_f32_e32 v124, v124, v124
	v_max_f32_e32 v0, v0, v0
	v_max_f32_e32 v0, v0, v124
	v_mov_b32_e32 v124, v0
	s_nop 1
	v_permlane32_swap_b32_e32 v0, v124
	v_max3_f32 v0, v0, v124, 0
	v_exp_f32_e64 v124, -v0
	v_pk_add_f32 v[122:123], v[122:123], v[0:1] op_sel_hi:[1,0] neg_lo:[0,1] neg_hi:[0,1]
	v_pk_add_f32 v[120:121], v[120:121], v[0:1] op_sel_hi:[1,0] neg_lo:[0,1] neg_hi:[0,1]
	v_pk_add_f32 v[116:117], v[116:117], v[0:1] op_sel_hi:[1,0] neg_lo:[0,1] neg_hi:[0,1]
	v_pk_add_f32 v[118:119], v[118:119], v[0:1] op_sel_hi:[1,0] neg_lo:[0,1] neg_hi:[0,1]
	v_pk_add_f32 v[114:115], v[114:115], v[0:1] op_sel_hi:[1,0] neg_lo:[0,1] neg_hi:[0,1]
	v_pk_add_f32 v[112:113], v[112:113], v[0:1] op_sel_hi:[1,0] neg_lo:[0,1] neg_hi:[0,1]
	v_pk_add_f32 v[110:111], v[110:111], v[0:1] op_sel_hi:[1,0] neg_lo:[0,1] neg_hi:[0,1]
	v_pk_add_f32 v[2:3], v[2:3], v[0:1] op_sel_hi:[1,0] neg_lo:[0,1] neg_hi:[0,1]
	v_add_f32_e32 v102, v102, v0
	v_mul_f32_e32 v101, v101, v124
	v_pk_mul_f32 v[50:51], v[50:51], v[124:125] op_sel_hi:[1,0]
	v_pk_mul_f32 v[48:49], v[48:49], v[124:125] op_sel_hi:[1,0]
	v_pk_mul_f32 v[42:43], v[42:43], v[124:125] op_sel_hi:[1,0]
	v_pk_mul_f32 v[40:41], v[40:41], v[124:125] op_sel_hi:[1,0]
	v_pk_mul_f32 v[34:35], v[34:35], v[124:125] op_sel_hi:[1,0]
	v_pk_mul_f32 v[32:33], v[32:33], v[124:125] op_sel_hi:[1,0]
	v_pk_mul_f32 v[26:27], v[26:27], v[124:125] op_sel_hi:[1,0]
	v_pk_mul_f32 v[24:25], v[24:25], v[124:125] op_sel_hi:[1,0]
; DEVI float xmax16(float x) { auto r = __builtin_amdgcn_permlane16_swap(__float_as_uint(x), __float_as_uint(x), false, false); return fmaxf(__uint_as_float(r[0]), __uint_as_float(r[1])); }
; DEVI float xmax32(float x) { auto r = __builtin_amdgcn_permlane32_swap(__float_as_uint(x), __float_as_uint(x), false, false); return fmaxf(__uint_as_float(r[0]), __uint_as_float(r[1])); }
; template <int DK, int QB, bool NA>
; DEVI void attn_item(const AttnArgs& a, unsigned char* smem) {
;     ...
;           const f32x2 scv = {a.sc2, a.sc2}, nmv = {-m[qb], -m[qb]};
;           f32x2 t[4][2];
; #pragma unroll
;           for (int kb = 0; kb < 4; ++kb)
; #pragma unroll
;             for (int h = 0; h < 2; ++h) {
;               const f32x2 sv = {s[kb][qb][2 * h], s[kb][qb][2 * h + 1]};
;               t[kb][h] = sv * scv + nmv;
;             }
;           float mx = fmaxf(t[0][0].x, t[0][0].y);
; #pragma unroll
;           for (int kb = 0; kb < 4; ++kb)
; #pragma unroll
;             for (int h = 0; h < 2; ++h) mx = fmaxf(mx, fmaxf(t[kb][h].x, t[kb][h].y));
;           if (j == 0 || __any(mx > 6.f)) {
;             mx = xmax32(xmax16(mx));
;             const float d = (j == 0) ? mx : fmaxf(mx, 0.f);
;             const float alpha = __builtin_amdgcn_exp2f(-d);
;             const f32x2 dv = {d, d};
; #pragma unroll
;             for (int kb = 0; kb < 4; ++kb)
; #pragma unroll
;               for (int h = 0; h < 2; ++h) t[kb][h] -= dv;
;             m[qb] += d;
;             l[qb] *= alpha;
; #pragma unroll
;             for (int db = 0; db < 4; ++db) o[db][qb] *= alpha;
;           }
.LBB0_2272:
	v_mov_b32_e32 v0, v103
	v_fma_f32 v98, v98, s92, -v0
	v_fma_f32 v99, v99, s92, -v0
	v_fma_f32 v124, v96, s92, -v0
	v_fma_f32 v125, v97, s92, -v0
	v_fma_f32 v96, v92, s92, -v0
	v_fma_f32 v97, v93, s92, -v0
	v_fma_f32 v94, v94, s92, -v0
	v_fma_f32 v95, v95, s92, -v0
	v_fma_f32 v92, v88, s92, -v0
	v_fma_f32 v93, v89, s92, -v0
	v_fma_f32 v90, v90, s92, -v0
	v_fma_f32 v91, v91, s92, -v0
	v_fma_f32 v88, v84, s92, -v0
	v_fma_f32 v89, v85, s92, -v0
	v_fma_f32 v84, v86, s92, -v0
	v_fma_f32 v85, v87, s92, -v0
	v_max_f32_e32 v0, v98, v99
	v_max3_f32 v0, v124, v125, v0
	v_max_f32_e32 v86, v96, v97
	v_max_f32_e32 v87, v94, v95
	v_max3_f32 v0, v0, v86, v87
	v_max_f32_e32 v86, v92, v93
	v_max_f32_e32 v87, v90, v91
	v_max3_f32 v0, v0, v86, v87
	v_max_f32_e32 v86, v88, v89
	v_max_f32_e32 v87, v84, v85
	v_max3_f32 v0, v0, v86, v87
	v_cmp_lt_f32_e32 vcc, s20, v0
	s_cbranch_vccz .LBB0_2267
	v_mov_b32_e32 v86, v0
	s_nop 1
	v_permlane16_swap_b32_e32 v0, v86
	v_max_f32_e32 v86, v86, v86
	v_max_f32_e32 v0, v0, v0
	v_max_f32_e32 v0, v0, v86
	v_mov_b32_e32 v86, v0
	s_nop 1
	v_permlane32_swap_b32_e32 v0, v86
	v_max3_f32 v0, v0, v86, 0
	v_exp_f32_e64 v86, -v0
	v_pk_add_f32 v[124:125], v[124:125], v[0:1] op_sel_hi:[1,0] neg_lo:[0,1] neg_hi:[0,1]
	v_pk_add_f32 v[98:99], v[98:99], v[0:1] op_sel_hi:[1,0] neg_lo:[0,1] neg_hi:[0,1]
	v_pk_add_f32 v[96:97], v[96:97], v[0:1] op_sel_hi:[1,0] neg_lo:[0,1] neg_hi:[0,1]
	v_pk_add_f32 v[94:95], v[94:95], v[0:1] op_sel_hi:[1,0] neg_lo:[0,1] neg_hi:[0,1]
	v_pk_add_f32 v[92:93], v[92:93], v[0:1] op_sel_hi:[1,0] neg_lo:[0,1] neg_hi:[0,1]
	v_pk_add_f32 v[90:91], v[90:91], v[0:1] op_sel_hi:[1,0] neg_lo:[0,1] neg_hi:[0,1]
	v_pk_add_f32 v[88:89], v[88:89], v[0:1] op_sel_hi:[1,0] neg_lo:[0,1] neg_hi:[0,1]
	v_pk_add_f32 v[84:85], v[84:85], v[0:1] op_sel_hi:[1,0] neg_lo:[0,1] neg_hi:[0,1]
	v_add_f32_e32 v103, v103, v0
	v_mul_f32_e32 v100, v100, v86
	v_pk_mul_f32 v[46:47], v[46:47], v[86:87] op_sel_hi:[1,0]
	v_pk_mul_f32 v[44:45], v[44:45], v[86:87] op_sel_hi:[1,0]
	v_pk_mul_f32 v[38:39], v[38:39], v[86:87] op_sel_hi:[1,0]
	v_pk_mul_f32 v[36:37], v[36:37], v[86:87] op_sel_hi:[1,0]
	v_pk_mul_f32 v[30:31], v[30:31], v[86:87] op_sel_hi:[1,0]
	v_pk_mul_f32 v[28:29], v[28:29], v[86:87] op_sel_hi:[1,0]
	v_pk_mul_f32 v[22:23], v[22:23], v[86:87] op_sel_hi:[1,0]
	v_pk_mul_f32 v[20:21], v[20:21], v[86:87] op_sel_hi:[1,0]
	s_branch .LBB0_2267

; template <int DK, int QB, bool NA>
; DEVI void attn_item(const AttnArgs& a, unsigned char* smem) {
;     ...
;   for (int j = 0; j < nt; ++j) {
;     if (j + 1 < nt) {
;       if constexpr (DK == 96) asm volatile("s_waitcnt vmcnt(5)" ::: "memory");
;       else                    asm volatile("s_waitcnt vmcnt(4)" ::: "memory");
;     } else {
;       asm volatile("s_waitcnt vmcnt(0)" ::: "memory");
;     }
;     RAW_BARRIER();
;     if (j + 2 < nt) ATT_ISSUE(j + 2, is);
;     is = (is + 1 == S) ? 0 : is + 1;
;     const unsigned cur = lbase + cs * ATT_STAGE;
;     cs = (cs + 1 == S) ? 0 : cs + 1;
;     if (wact) {
;       f32x4 s[4][QB];
; #pragma unroll
;       for (int kb = 0; kb < 4; ++kb)
; #pragma unroll
;         for (int qb = 0; qb < QB; ++qb) s[kb][qb] = (f32x4){0.f, 0.f, 0.f, 0.f};
;       {
;         bf16x8 k0[4], k1[4], k2[4];
;         const unsigned a0 = cur + ka0, a1 = cur + ka1, a2 = cur + kr;
;         k0[0] = ldsr<0>(a0); k0[1] = ldsr<2048>(a0); k0[2] = ldsr<4096>(a0); k0[3] = ldsr<6144>(a0);
;         k1[0] = ldsr<0>(a1); k1[1] = ldsr<2048>(a1); k1[2] = ldsr<4096>(a1); k1[3] = ldsr<6144>(a1);
;         if constexpr (KS == 3) { k2[0] = ldsr<0>(a2); k2[1] = ldsr<1024>(a2); k2[2] = ldsr<2048>(a2); k2[3] = ldsr<3072>(a2); }
;         if constexpr (KS == 3) asm volatile("s_waitcnt lgkmcnt(8)" : "+v"(k0[0]), "+v"(k0[1]), "+v"(k0[2]), "+v"(k0[3]) :: "memory");
;         else                   asm volatile("s_waitcnt lgkmcnt(4)" : "+v"(k0[0]), "+v"(k0[1]), "+v"(k0[2]), "+v"(k0[3]) :: "memory");
;         __builtin_amdgcn_sched_barrier(0);
; #pragma unroll
;         for (int kb = 0; kb < 4; ++kb)
; #pragma unroll
;           for (int qb = 0; qb < QB; ++qb) s[kb][qb] = __builtin_amdgcn_mfma_f32_16x16x32_bf16(k0[kb], qf[qb][0], s[kb][qb], 0, 0, 0);
;         if constexpr (KS == 3) asm volatile("s_waitcnt lgkmcnt(4)" : "+v"(k1[0]), "+v"(k1[1]), "+v"(k1[2]), "+v"(k1[3]) :: "memory");
;         else                   asm volatile("s_waitcnt lgkmcnt(0)" : "+v"(k1[0]), "+v"(k1[1]), "+v"(k1[2]), "+v"(k1[3]) :: "memory");
;         __builtin_amdgcn_sched_barrier(0);
; #pragma unroll
;         for (int kb = 0; kb < 4; ++kb)
; #pragma unroll
;           for (int qb = 0; qb < QB; ++qb) s[kb][qb] = __builtin_amdgcn_mfma_f32_16x16x32_bf16(k1[kb], qf[qb][1], s[kb][qb], 0, 0, 0);
;         if constexpr (KS == 3) {
.LBB0_2292:
	s_and_saveexec_b64 s[42:43], s[0:1]
	s_cbranch_execz .LBB0_2298
	s_mul_i32 s8, s3, 0x5000
	v_or_b32_e32 v0, s8, v183
	ds_read_b128 v[52:55], v0 offset:0
	ds_read_b128 v[56:59], v0 offset:0x800
	ds_read_b128 v[60:63], v0 offset:0x1000
	ds_read_b128 v[64:67], v0 offset:0x1800
	v_or_b32_e32 v2, s8, v184
	ds_read_b128 v[68:71], v2 offset:0
	ds_read_b128 v[72:75], v2 offset:0x800
	ds_read_b128 v[76:79], v2 offset:0x1000
	ds_read_b128 v[80:83], v2 offset:0x1800
	s_waitcnt lgkmcnt(4)
	s_nop 0
	s_setprio 1
	v_mfma_f32_16x16x32_bf16 v[84:87], v[52:55], v[16:19], 0
	s_waitcnt lgkmcnt(0)
	v_mfma_f32_16x16x32_bf16 v[52:55], v[52:55], v[12:15], 0
	v_mfma_f32_16x16x32_bf16 v[88:91], v[56:59], v[16:19], 0
	v_mfma_f32_16x16x32_bf16 v[56:59], v[56:59], v[12:15], 0
	v_mfma_f32_16x16x32_bf16 v[104:107], v[60:63], v[16:19], 0
	v_mfma_f32_16x16x32_bf16 v[60:63], v[60:63], v[12:15], 0
	v_mfma_f32_16x16x32_bf16 v[108:111], v[64:67], v[16:19], 0
	v_mfma_f32_16x16x32_bf16 v[64:67], v[64:67], v[12:15], 0
	v_mfma_f32_16x16x32_bf16 v[112:115], v[68:71], v[8:11], v[84:87]
	v_add_u32_e32 v0, s8, v129
	v_add_u32_e32 v2, s8, v180
	v_add_u32_e32 v3, s8, v181
	v_mfma_f32_16x16x32_bf16 v[118:121], v[72:75], v[8:11], v[88:91]
	v_mfma_f32_16x16x32_bf16 v[104:107], v[76:79], v[8:11], v[104:107]
	s_nop 2
	v_fma_f32 v114, v114, s92, -v102
	v_fma_f32 v115, v115, s92, -v102
	v_fma_f32 v116, v112, s92, -v102
	v_fma_f32 v117, v113, s92, -v102
	s_nop 0
	v_fma_f32 v112, v120, s92, -v102
	v_fma_f32 v113, v121, s92, -v102
	v_mfma_f32_16x16x32_bf16 v[122:125], v[80:83], v[8:11], v[108:111]
	v_mfma_f32_16x16x32_bf16 v[96:99], v[68:71], v[4:7], v[52:55]
	s_nop 1
	v_fma_f32 v110, v118, s92, -v102
	v_fma_f32 v111, v119, s92, -v102
	v_fma_f32 v108, v104, s92, -v102
	v_fma_f32 v109, v105, s92, -v102
	v_fma_f32 v106, v106, s92, -v102
	v_fma_f32 v107, v107, s92, -v102
	v_mfma_f32_16x16x32_bf16 v[92:95], v[72:75], v[4:7], v[56:59]
	v_max_f32_e32 v118, v110, v111
	v_max_f32_e32 v119, v112, v113
	v_add_u32_e32 v54, s8, v182
	v_mfma_f32_16x16x32_bf16 v[88:91], v[76:79], v[4:7], v[60:63]
	v_fma_f32 v104, v122, s92, -v102
	v_fma_f32 v105, v123, s92, -v102
	s_mov_b32 s8, 0x40c00000
	v_mfma_f32_16x16x32_bf16 v[84:87], v[80:83], v[4:7], v[64:67]
	s_setprio 0
	ds_read_b64 v[80:81], v0 offset:0
	ds_read_b64 v[82:83], v2 offset:0
	ds_read_b64 v[76:77], v0 offset:0x800
	ds_read_b64 v[78:79], v2 offset:0x800
	ds_read_b64 v[72:73], v0 offset:0x1000
	ds_read_b64 v[74:75], v2 offset:0x1000
	ds_read_b64 v[68:69], v0 offset:0x1800
	v_max_f32_e32 v0, v114, v115
	v_max3_f32 v0, v116, v117, v0
	ds_read_b64 v[70:71], v2 offset:0x1800
	ds_read_b64 v[64:65], v3 offset:0
	ds_read_b64 v[66:67], v54 offset:0
	ds_read_b64 v[60:61], v3 offset:0x800
	ds_read_b64 v[62:63], v54 offset:0x800
	ds_read_b64 v[56:57], v3 offset:0x1000
	ds_read_b64 v[58:59], v54 offset:0x1000
	ds_read_b64 v[52:53], v3 offset:0x1800
	v_fma_f32 v2, v124, s92, -v102
	v_fma_f32 v3, v125, s92, -v102
	v_max3_f32 v0, v0, v118, v119
	v_max_f32_e32 v118, v108, v109
	v_max_f32_e32 v119, v106, v107
	v_max3_f32 v0, v0, v118, v119
	v_max_f32_e32 v118, v104, v105
	v_max_f32_e32 v119, v2, v3
	v_max3_f32 v0, v0, v118, v119
	v_cmp_lt_f32_e32 vcc, s8, v0
	ds_read_b64 v[54:55], v54 offset:0x1800
	s_cbranch_vccz .LBB0_2295
	v_mov_b32_e32 v118, v0
	s_nop 1
	v_permlane16_swap_b32_e32 v0, v118
	v_max_f32_e32 v118, v118, v118
	v_max_f32_e32 v0, v0, v0
	v_max_f32_e32 v0, v0, v118
	v_mov_b32_e32 v118, v0
	s_nop 1
	v_permlane32_swap_b32_e32 v0, v118
	v_max3_f32 v0, v0, v118, 0
	v_exp_f32_e64 v118, -v0
	v_pk_add_f32 v[116:117], v[116:117], v[0:1] op_sel_hi:[1,0] neg_lo:[0,1] neg_hi:[0,1]
	v_pk_add_f32 v[114:115], v[114:115], v[0:1] op_sel_hi:[1,0] neg_lo:[0,1] neg_hi:[0,1]
	v_pk_add_f32 v[110:111], v[110:111], v[0:1] op_sel_hi:[1,0] neg_lo:[0,1] neg_hi:[0,1]
	v_pk_add_f32 v[112:113], v[112:113], v[0:1] op_sel_hi:[1,0] neg_lo:[0,1] neg_hi:[0,1]
	v_pk_add_f32 v[108:109], v[108:109], v[0:1] op_sel_hi:[1,0] neg_lo:[0,1] neg_hi:[0,1]
	v_pk_add_f32 v[106:107], v[106:107], v[0:1] op_sel_hi:[1,0] neg_lo:[0,1] neg_hi:[0,1]
	v_pk_add_f32 v[104:105], v[104:105], v[0:1] op_sel_hi:[1,0] neg_lo:[0,1] neg_hi:[0,1]
	v_pk_add_f32 v[2:3], v[2:3], v[0:1] op_sel_hi:[1,0] neg_lo:[0,1] neg_hi:[0,1]
	v_add_f32_e32 v102, v102, v0
	v_mul_f32_e32 v101, v101, v118
	v_pk_mul_f32 v[50:51], v[50:51], v[118:119] op_sel_hi:[1,0]
	v_pk_mul_f32 v[48:49], v[48:49], v[118:119] op_sel_hi:[1,0]
	v_pk_mul_f32 v[42:43], v[42:43], v[118:119] op_sel_hi:[1,0]
	v_pk_mul_f32 v[40:41], v[40:41], v[118:119] op_sel_hi:[1,0]
	v_pk_mul_f32 v[34:35], v[34:35], v[118:119] op_sel_hi:[1,0]
	v_pk_mul_f32 v[32:33], v[32:33], v[118:119] op_sel_hi:[1,0]
	v_pk_mul_f32 v[26:27], v[26:27], v[118:119] op_sel_hi:[1,0]
	v_pk_mul_f32 v[24:25], v[24:25], v[118:119] op_sel_hi:[1,0]
; DEVI float xmax16(float x) { auto r = __builtin_amdgcn_permlane16_swap(__float_as_uint(x), __float_as_uint(x), false, false); return fmaxf(__uint_as_float(r[0]), __uint_as_float(r[1])); }
; DEVI float xmax32(float x) { auto r = __builtin_amdgcn_permlane32_swap(__float_as_uint(x), __float_as_uint(x), false, false); return fmaxf(__uint_as_float(r[0]), __uint_as_float(r[1])); }
; template <int DK, int QB, bool NA>
; DEVI void attn_item(const AttnArgs& a, unsigned char* smem) {
;     ...
;           const f32x2 scv = {a.sc2, a.sc2}, nmv = {-m[qb], -m[qb]};
;           f32x2 t[4][2];
; #pragma unroll
;           for (int kb = 0; kb < 4; ++kb)
; #pragma unroll
;             for (int h = 0; h < 2; ++h) {
;               const f32x2 sv = {s[kb][qb][2 * h], s[kb][qb][2 * h + 1]};
;               t[kb][h] = sv * scv + nmv;
;             }
;           float mx = fmaxf(t[0][0].x, t[0][0].y);
; #pragma unroll
;           for (int kb = 0; kb < 4; ++kb)
; #pragma unroll
;             for (int h = 0; h < 2; ++h) mx = fmaxf(mx, fmaxf(t[kb][h].x, t[kb][h].y));
;           if (j == 0 || __any(mx > 6.f)) {
;             mx = xmax32(xmax16(mx));
;             const float d = (j == 0) ? mx : fmaxf(mx, 0.f);
;             const float alpha = __builtin_amdgcn_exp2f(-d);
;             const f32x2 dv = {d, d};
; #pragma unroll
;             for (int kb = 0; kb < 4; ++kb)
; #pragma unroll
;               for (int h = 0; h < 2; ++h) t[kb][h] -= dv;
;             m[qb] += d;
;             l[qb] *= alpha;
; #pragma unroll
;             for (int db = 0; db < 4; ++db) o[db][qb] *= alpha;
;           }
.LBB0_2295:
	v_mov_b32_e32 v0, v103
	v_fma_f32 v98, v98, s92, -v0
	v_fma_f32 v99, v99, s92, -v0
	v_fma_f32 v118, v96, s92, -v0
	v_fma_f32 v119, v97, s92, -v0
	v_fma_f32 v96, v92, s92, -v0
	v_fma_f32 v97, v93, s92, -v0
	v_fma_f32 v94, v94, s92, -v0
	v_fma_f32 v95, v95, s92, -v0
	v_fma_f32 v92, v88, s92, -v0
	v_fma_f32 v93, v89, s92, -v0
	v_fma_f32 v90, v90, s92, -v0
	v_fma_f32 v91, v91, s92, -v0
	v_fma_f32 v88, v84, s92, -v0
	v_fma_f32 v89, v85, s92, -v0
	v_fma_f32 v84, v86, s92, -v0
	v_fma_f32 v85, v87, s92, -v0
	v_max_f32_e32 v0, v98, v99
	v_max3_f32 v0, v118, v119, v0
	v_max_f32_e32 v86, v96, v97
	v_max_f32_e32 v87, v94, v95
	v_max3_f32 v0, v0, v86, v87
	v_max_f32_e32 v86, v92, v93
	v_max_f32_e32 v87, v90, v91
	v_max3_f32 v0, v0, v86, v87
	v_max_f32_e32 v86, v88, v89
	v_max_f32_e32 v87, v84, v85
	v_max3_f32 v0, v0, v86, v87
	v_cmp_lt_f32_e32 vcc, s8, v0
	s_cbranch_vccz .LBB0_2297
	v_mov_b32_e32 v86, v0
	s_nop 1
	v_permlane16_swap_b32_e32 v0, v86
	v_max_f32_e32 v86, v86, v86
	v_max_f32_e32 v0, v0, v0
	v_max_f32_e32 v0, v0, v86
	v_mov_b32_e32 v86, v0
	s_nop 1
	v_permlane32_swap_b32_e32 v0, v86
	v_max3_f32 v0, v0, v86, 0
	v_exp_f32_e64 v86, -v0
	v_pk_add_f32 v[118:119], v[118:119], v[0:1] op_sel_hi:[1,0] neg_lo:[0,1] neg_hi:[0,1]
	v_pk_add_f32 v[98:99], v[98:99], v[0:1] op_sel_hi:[1,0] neg_lo:[0,1] neg_hi:[0,1]
	v_pk_add_f32 v[96:97], v[96:97], v[0:1] op_sel_hi:[1,0] neg_lo:[0,1] neg_hi:[0,1]
	v_pk_add_f32 v[94:95], v[94:95], v[0:1] op_sel_hi:[1,0] neg_lo:[0,1] neg_hi:[0,1]
	v_pk_add_f32 v[92:93], v[92:93], v[0:1] op_sel_hi:[1,0] neg_lo:[0,1] neg_hi:[0,1]
	v_pk_add_f32 v[90:91], v[90:91], v[0:1] op_sel_hi:[1,0] neg_lo:[0,1] neg_hi:[0,1]
	v_pk_add_f32 v[88:89], v[88:89], v[0:1] op_sel_hi:[1,0] neg_lo:[0,1] neg_hi:[0,1]
	v_pk_add_f32 v[84:85], v[84:85], v[0:1] op_sel_hi:[1,0] neg_lo:[0,1] neg_hi:[0,1]
	v_add_f32_e32 v103, v103, v0
	v_mul_f32_e32 v100, v100, v86
	v_pk_mul_f32 v[46:47], v[46:47], v[86:87] op_sel_hi:[1,0]
	v_pk_mul_f32 v[44:45], v[44:45], v[86:87] op_sel_hi:[1,0]
	v_pk_mul_f32 v[38:39], v[38:39], v[86:87] op_sel_hi:[1,0]
	v_pk_mul_f32 v[36:37], v[36:37], v[86:87] op_sel_hi:[1,0]
	v_pk_mul_f32 v[30:31], v[30:31], v[86:87] op_sel_hi:[1,0]
	v_pk_mul_f32 v[28:29], v[28:29], v[86:87] op_sel_hi:[1,0]
	v_pk_mul_f32 v[22:23], v[22:23], v[86:87] op_sel_hi:[1,0]
	v_pk_mul_f32 v[20:21], v[20:21], v[86:87] op_sel_hi:[1,0]

; template <int DK, int QB, bool NA>
; DEVI void attn_item(const AttnArgs& a, unsigned char* smem) {
;     ...
;     if (j + 1 < nt) {
;       if constexpr (DK == 96) asm volatile("s_waitcnt vmcnt(5)" ::: "memory");
;       else                    asm volatile("s_waitcnt vmcnt(4)" ::: "memory");
;     } else {
;       asm volatile("s_waitcnt vmcnt(0)" ::: "memory");
;     }
;     RAW_BARRIER();
;     if (j + 2 < nt) ATT_ISSUE(j + 2, is);
;     is = (is + 1 == S) ? 0 : is + 1;
;     const unsigned cur = lbase + cs * ATT_STAGE;
;     cs = (cs + 1 == S) ? 0 : cs + 1;
;     if (wact) {
;       f32x4 s[4][QB];
; #pragma unroll
;       for (int kb = 0; kb < 4; ++kb)
; #pragma unroll
;         for (int qb = 0; qb < QB; ++qb) s[kb][qb] = (f32x4){0.f, 0.f, 0.f, 0.f};
;       {
;         bf16x8 k0[4], k1[4], k2[4];
;         const unsigned a0 = cur + ka0, a1 = cur + ka1, a2 = cur + kr;
;         k0[0] = ldsr<0>(a0); k0[1] = ldsr<2048>(a0); k0[2] = ldsr<4096>(a0); k0[3] = ldsr<6144>(a0);
;         k1[0] = ldsr<0>(a1); k1[1] = ldsr<2048>(a1); k1[2] = ldsr<4096>(a1); k1[3] = ldsr<6144>(a1);
;         if constexpr (KS == 3) { k2[0] = ldsr<0>(a2); k2[1] = ldsr<1024>(a2); k2[2] = ldsr<2048>(a2); k2[3] = ldsr<3072>(a2); }
;         if constexpr (KS == 3) asm volatile("s_waitcnt lgkmcnt(8)" : "+v"(k0[0]), "+v"(k0[1]), "+v"(k0[2]), "+v"(k0[3]) :: "memory");
;         else                   asm volatile("s_waitcnt lgkmcnt(4)" : "+v"(k0[0]), "+v"(k0[1]), "+v"(k0[2]), "+v"(k0[3]) :: "memory");
;         __builtin_amdgcn_sched_barrier(0);
; #pragma unroll
;         for (int kb = 0; kb < 4; ++kb)
; #pragma unroll
;           for (int qb = 0; qb < QB; ++qb) s[kb][qb] = __builtin_amdgcn_mfma_f32_16x16x32_bf16(k0[kb], qf[qb][0], s[kb][qb], 0, 0, 0);
;         if constexpr (KS == 3) asm volatile("s_waitcnt lgkmcnt(4)" : "+v"(k1[0]), "+v"(k1[1]), "+v"(k1[2]), "+v"(k1[3]) :: "memory");
;         else                   asm volatile("s_waitcnt lgkmcnt(0)" : "+v"(k1[0]), "+v"(k1[1]), "+v"(k1[2]), "+v"(k1[3]) :: "memory");
;         __builtin_amdgcn_sched_barrier(0);
; #pragma unroll
;         for (int kb = 0; kb < 4; ++kb)
; #pragma unroll
;           for (int qb = 0; qb < QB; ++qb) s[kb][qb] = __builtin_amdgcn_mfma_f32_16x16x32_bf16(k1[kb], qf[qb][1], s[kb][qb], 0, 0, 0);
;         if constexpr (KS == 3) {
.LBB0_2298:
	s_or_b64 exec, exec, s[42:43]
	s_waitcnt vmcnt(0)
	s_waitcnt lgkmcnt(0)
	s_mov_b64 s[42:43], 0
	s_mov_b64 s[52:53], 0
	s_barrier
	s_and_saveexec_b64 s[54:55], s[0:1]
	s_cbranch_execz .LBB0_2308
	s_add_i32 s0, s3, 1
	s_mul_i32 s1, s0, 0x5000
	s_cmp_lg_u32 s0, 3
	s_cselect_b32 s0, s1, 0
	v_or_b32_e32 v0, s0, v183
	ds_read_b128 v[52:55], v0 offset:0
	ds_read_b128 v[56:59], v0 offset:0x800
	ds_read_b128 v[60:63], v0 offset:0x1000
	ds_read_b128 v[64:67], v0 offset:0x1800
	v_or_b32_e32 v2, s0, v184
	ds_read_b128 v[68:71], v2 offset:0
	ds_read_b128 v[72:75], v2 offset:0x800
	ds_read_b128 v[76:79], v2 offset:0x1000
	ds_read_b128 v[80:83], v2 offset:0x1800
	s_waitcnt lgkmcnt(4)
	s_nop 0
	s_setprio 1
	v_mfma_f32_16x16x32_bf16 v[16:19], v[52:55], v[16:19], 0
	s_waitcnt lgkmcnt(0)
	v_mfma_f32_16x16x32_bf16 v[12:15], v[52:55], v[12:15], 0
	v_mfma_f32_16x16x32_bf16 v[74:77], v[68:71], v[8:11], v[16:19]
	v_add_u32_e32 v2, s0, v180
	v_add_u32_e32 v3, s0, v181
	v_add_u32_e32 v0, s0, v129
	s_nop 2
	v_add_u32_e32 v18, s0, v182
	ds_read_b64 v[64:65], v0 offset:0
	v_mfma_f32_16x16x32_bf16 v[68:71], v[68:71], v[4:7], v[12:15]
	s_setprio 0
	ds_read_b64 v[66:67], v2 offset:0
	ds_read_b64 v[60:61], v0 offset:0x800
	ds_read_b64 v[62:63], v2 offset:0x800
	ds_read_b64 v[56:57], v0 offset:0x1000
	ds_read_b64 v[58:59], v2 offset:0x1000
	ds_read_b64 v[52:53], v0 offset:0x1800
	ds_read_b64 v[54:55], v2 offset:0x1800
	ds_read_b64 v[14:15], v3 offset:0
	ds_read_b64 v[16:17], v18 offset:0
	ds_read_b64 v[10:11], v3 offset:0x800
	ds_read_b64 v[12:13], v18 offset:0x800
	ds_read_b64 v[6:7], v3 offset:0x1000
	ds_read_b64 v[8:9], v18 offset:0x1000
	ds_read_b64 v[2:3], v3 offset:0x1800
	ds_read_b64 v[4:5], v18 offset:0x1800
	v_fma_f32 v74, v74, s92, -v102
	v_fma_f32 v75, v75, s92, -v102
	v_fma_f32 v72, v76, s92, -v102
	v_fma_f32 v73, v77, s92, -v102
	v_sub_f32_e32 v18, 0xf011accb, v102
	v_max_f32_e32 v0, v74, v75
	v_max_f32_e32 v19, v72, v73
	v_max_f32_e32 v76, v18, v18
	v_max3_f32 v0, v0, v19, v76
	s_mov_b32 s0, 0x40c00000
	v_mov_b32_e32 v19, v18
	v_cmp_lt_f32_e32 vcc, s0, v0
	s_cbranch_vccz .LBB0_2301
	v_mov_b32_e32 v76, v0
	s_nop 1
	v_permlane16_swap_b32_e32 v0, v76
	v_max_f32_e32 v76, v76, v76
	v_max_f32_e32 v0, v0, v0
	v_max_f32_e32 v0, v0, v76
	v_mov_b32_e32 v76, v0
	s_nop 1
	v_permlane32_swap_b32_e32 v0, v76
	v_max3_f32 v0, v0, v76, 0
	v_exp_f32_e64 v76, -v0
	v_pk_add_f32 v[74:75], v[74:75], v[0:1] op_sel_hi:[1,0] neg_lo:[0,1] neg_hi:[0,1]
	v_pk_add_f32 v[72:73], v[72:73], v[0:1] op_sel_hi:[1,0] neg_lo:[0,1] neg_hi:[0,1]
	v_pk_add_f32 v[18:19], v[18:19], v[0:1] op_sel_hi:[1,0] neg_lo:[0,1] neg_hi:[0,1]
	v_mul_f32_e32 v101, v101, v76
	v_pk_mul_f32 v[50:51], v[50:51], v[76:77] op_sel_hi:[1,0]
	v_pk_mul_f32 v[48:49], v[48:49], v[76:77] op_sel_hi:[1,0]
	v_pk_mul_f32 v[42:43], v[42:43], v[76:77] op_sel_hi:[1,0]
	v_pk_mul_f32 v[40:41], v[40:41], v[76:77] op_sel_hi:[1,0]
	v_pk_mul_f32 v[34:35], v[34:35], v[76:77] op_sel_hi:[1,0]
	v_pk_mul_f32 v[32:33], v[32:33], v[76:77] op_sel_hi:[1,0]
	v_pk_mul_f32 v[26:27], v[26:27], v[76:77] op_sel_hi:[1,0]
	v_pk_mul_f32 v[24:25], v[24:25], v[76:77] op_sel_hi:[1,0]
.LBB0_2301:
	v_mov_b32_e32 v0, v103
	v_fma_f32 v68, v68, s92, -v0
	v_fma_f32 v69, v69, s92, -v0
	v_fma_f32 v76, v70, s92, -v0
	v_fma_f32 v77, v71, s92, -v0
	v_sub_f32_e32 v70, 0xf011accb, v103
	v_max_f32_e32 v0, v68, v69
	v_max_f32_e32 v71, v76, v77
	v_max_f32_e32 v78, v70, v70
	v_max3_f32 v0, v0, v71, v78
	v_mov_b32_e32 v71, v70
	v_cmp_lt_f32_e32 vcc, s0, v0
	s_cbranch_vccz .LBB0_2303
	v_mov_b32_e32 v78, v0
	s_nop 1
	v_permlane16_swap_b32_e32 v0, v78
	v_max_f32_e32 v78, v78, v78
	v_max_f32_e32 v0, v0, v0
	v_max_f32_e32 v0, v0, v78
	v_mov_b32_e32 v78, v0
	s_nop 1
	v_permlane32_swap_b32_e32 v0, v78
	v_max3_f32 v0, v0, v78, 0
	v_exp_f32_e64 v78, -v0
	v_pk_add_f32 v[68:69], v[68:69], v[0:1] op_sel_hi:[1,0] neg_lo:[0,1] neg_hi:[0,1]
	v_pk_add_f32 v[76:77], v[76:77], v[0:1] op_sel_hi:[1,0] neg_lo:[0,1] neg_hi:[0,1]
	v_pk_add_f32 v[70:71], v[70:71], v[0:1] op_sel_hi:[1,0] neg_lo:[0,1] neg_hi:[0,1]
	v_mul_f32_e32 v100, v100, v78
	v_pk_mul_f32 v[46:47], v[46:47], v[78:79] op_sel_hi:[1,0]
	v_pk_mul_f32 v[44:45], v[44:45], v[78:79] op_sel_hi:[1,0]
	v_pk_mul_f32 v[38:39], v[38:39], v[78:79] op_sel_hi:[1,0]
	v_pk_mul_f32 v[36:37], v[36:37], v[78:79] op_sel_hi:[1,0]
	v_pk_mul_f32 v[30:31], v[30:31], v[78:79] op_sel_hi:[1,0]
	v_pk_mul_f32 v[28:29], v[28:29], v[78:79] op_sel_hi:[1,0]
	v_pk_mul_f32 v[22:23], v[22:23], v[78:79] op_sel_hi:[1,0]
	v_pk_mul_f32 v[20:21], v[20:21], v[78:79] op_sel_hi:[1,0]

; #define RAW_BARRIER() do { asm volatile("s_waitcnt lgkmcnt(0)" ::: "memory"); __builtin_amdgcn_s_barrier(); } while (0)
; template <int DK, int QB, bool NA>
; DEVI void attn_item(const AttnArgs& a, unsigned char* smem) {
;     ...
;   bf16x8 qf[QB][KS];
; #pragma unroll
;   for (int qb = 0; qb < QB; ++qb) {
;     const bf16_t* qp = a.Q + (size_t)((wact ? w * QB * 16 : 0) + qb * 16 + l16) * a.ldq + g * 8;
; #pragma unroll
;     for (int ks = 0; ks < KS; ++ks) qf[qb][ks] = *(const bf16x8*)(qp + ks * 32);
;   }
;   float m[QB], l[QB];
;   f32x4 o[4][QB];
; #pragma unroll
;   for (int qb = 0; qb < QB; ++qb) {
;     m[qb] = NA ? -1e30f : 0.f; l[qb] = 0.f;
; #pragma unroll
;     for (int db = 0; db < 4; ++db) o[db][qb] = (f32x4){0.f, 0.f, 0.f, 0.f};
;   }
;   const int r8 = tid >> 3, c8 = (tid & 7) ^ ((tid >> 4) & 7);
;   const bf16_t* Kn = a.K + (size_t)r8 * a.ldk + c8 * 8;
;   const bf16_t* Kr = a.K + (size_t)(tid >> 2) * a.ldk + 64 + (((tid & 3) ^ ((0 - (tid >> 4)) & 3)) * 8);
;   const bf16_t* Vg = a.Vt + (size_t)r8 * a.Lk + c8 * 8;
;   const size_t kstep = (size_t)32 * a.ldk, vstep = (size_t)32 * a.Lk;
;   unsigned char* lds_t = smem + tid * 16;
;     ...
;   asm volatile("s_waitcnt vmcnt(0)" ::: "memory");
;   RAW_BARRIER();
;   ATT_ISSUE(0, 0);
;   if (nt > 1) ATT_ISSUE(1, 1);
;   const int sw8 = (l16 >> 1) & 7, vsw = sw8 << 1;
;   const unsigned ka0 = l16 * 128 + ((g ^ sw8) << 4), ka1 = l16 * 128 + (((4 + g) ^ sw8) << 4);
;   const unsigned kr = 8192 + l16 * 64 + ((g ^ ((0 - (l16 >> 2)) & 3)) << 4);
;   const unsigned vb00 = 12288 + l16 * 128 + (((0 + g) ^ vsw) << 3), vb01 = 12288 + l16 * 128 + (((4 + g) ^ vsw) << 3);
;   const unsigned vb10 = 12288 + l16 * 128 + (((8 + g) ^ vsw) << 3), vb11 = 12288 + l16 * 128 + (((12 + g) ^ vsw) << 3);
;   const unsigned biasA = lbase + ATT_BIAS_OFF;
;   const int qc = w * 16 + l16;
;   const int cs0 = min(max(qc - 8, 0), 48);
;   int cs = 0, is = 2;
; DEVI void attn_dense_phase(const Params& p, unsigned char* smem, unsigned* ctr) {
;     ...
;     if (h16 < 8) {
;       a.Q = Hb + H_QA + (size_t)q0 * 768 + h16 * 96; a.ldq = 768;
;       a.K = Hb + H_KMLA + (size_t)kb * 768 + h16 * 96; a.ldk = 768;
;       a.Vt = Hb + H_VTM + (size_t)512 * kb + (size_t)(h16 * 64) * Lk;
;       a.sc2 = 0.10206207261596577f * LOG2E;
;       attn_item<96, 2, false>(a, smem);
.LBB0_2309:
	s_mul_i32 s1, s59, 0x600
	v_readlane_b32 s3, v251, 58
	s_mul_hi_i32 s0, s59, 0x600
	s_add_u32 s3, s3, s1
	v_readlane_b32 s1, v251, 59
	s_mul_i32 s20, s58, 0x60
	s_addc_u32 s9, s1, s0
	s_lshl_b64 s[0:1], s[20:21], 1
	s_add_u32 s8, s3, s0
	s_addc_u32 s9, s9, s1
	s_ashr_i32 s3, s2, 31
	s_mul_i32 s40, s2, 0x600
	v_readlane_b32 s28, v251, 60
	s_mul_hi_i32 s20, s2, 0x600
	s_add_u32 s40, s28, s40
	v_readlane_b32 s28, v251, 61
	s_addc_u32 s20, s28, s20
	s_add_u32 s40, s40, s0
	s_addc_u32 s41, s20, s1
	s_lshl_b64 s[0:1], s[2:3], 10
	v_readlane_b32 s2, v251, 62
	s_add_u32 s2, s2, s0
	v_readlane_b32 s0, v251, 63
	s_mul_i32 s20, s62, s56
	v_mov_b32_e32 v2, v177
	s_addc_u32 s3, s0, s1
	s_lshl_b64 s[0:1], s[20:21], 1
	s_add_u32 s2, s2, s0
	v_ashrrev_i32_e32 v0, 1, v2
	v_and_b32_e32 v208, 0xffffffe0, v0
	s_addc_u32 s3, s3, s1
	v_cmp_gt_i32_e64 s[0:1], s57, v208
	v_and_b32_e32 v186, 15, v2
	v_bfe_u32 v187, v2, 4, 2
	v_cndmask_b32_e64 v0, 0, v208, s[0:1]
	v_or_b32_e32 v3, v0, v186
	v_lshlrev_b32_e32 v0, 4, v187
	v_lshl_add_u64 v[4:5], s[8:9], 0, v[0:1]
	s_movk_i32 s20, 0x600
	v_or_b32_e32 v0, 16, v3
	v_ashrrev_i32_e32 v32, 4, v2
	v_mad_i64_i32 v[6:7], s[8:9], v3, s20, v[4:5]
	v_mad_i64_i32 v[4:5], s[8:9], v0, s20, v[4:5]
	v_xor_b32_e32 v0, v32, v2
	v_ashrrev_i32_e32 v3, 3, v2
	v_mov_b64_e32 v[28:29], s[40:41]
	v_lshlrev_b32_e32 v0, 4, v0
	v_mad_i64_i32 v[30:31], s[8:9], v3, s20, v[28:29]
	v_and_b32_e32 v0, 0x70, v0
	v_lshl_add_u64 v[114:115], v[30:31], 0, v[0:1]
	v_ashrrev_i32_e32 v30, 2, v2
	v_mad_i64_i32 v[28:29], s[8:9], v30, s20, v[28:29]
	v_sub_u32_e32 v30, 0, v32
	v_xor_b32_e32 v30, v2, v30
	v_lshlrev_b32_e32 v30, 4, v30
	v_and_b32_e32 v30, 48, v30
	v_mov_b32_e32 v31, v1
	v_lshl_add_u64 v[116:117], v[28:29], 0, v[30:31]
	v_mad_i64_i32 v[30:31], s[8:9], v3, s62, 0
	v_lshl_add_u64 v[30:31], v[30:31], 1, s[2:3]
	v_lshlrev_b32_e32 v216, 4, v2
	v_lshl_add_u64 v[112:113], v[30:31], 0, v[0:1]
	v_readfirstlane_b32 s2, v216
	v_add_u32_e32 v0, 0x1000, v216
	global_load_dwordx4 v[24:27], v[6:7], off
	global_load_dwordx4 v[16:19], v[6:7], off offset:64
	global_load_dwordx4 v[8:11], v[6:7], off offset:128
	global_load_dwordx4 v[20:23], v[4:5], off
	global_load_dwordx4 v[12:15], v[4:5], off offset:64
	s_nop 0
	global_load_dwordx4 v[4:7], v[4:5], off offset:128
	s_waitcnt vmcnt(0)
	s_mov_b32 m0, s2
	v_readfirstlane_b32 s2, v0
	v_add_u32_e32 v0, 0x2000, v216
	s_mov_b64 s[40:41], 0x80
	s_waitcnt lgkmcnt(0)
	s_barrier
	global_load_lds_dwordx4 v[114:115], off
	v_lshl_add_u64 v[30:31], v[114:115], 0, s[86:87]
	s_mov_b32 m0, s2
	v_readfirstlane_b32 s2, v0
	v_add_u32_e32 v0, 0x3000, v216
	v_lshl_add_u64 v[28:29], v[116:117], 0, s[40:41]
	global_load_lds_dwordx4 v[30:31], off
	s_mov_b32 m0, s2
	v_readfirstlane_b32 s2, v0
	v_add_u32_e32 v0, 0x4000, v216
	global_load_lds_dwordx4 v[28:29], off
	s_mov_b32 m0, s2
	s_lshl_b32 s20, s62, 6
	v_readfirstlane_b32 s2, v0
	v_add_u32_e32 v0, 0x5000, v216
	global_load_lds_dwordx4 v[112:113], off
	v_lshl_add_u64 v[118:119], v[112:113], 0, s[20:21]
	s_mov_b32 m0, s2
	v_readfirstlane_b32 s2, v0
	global_load_lds_dwordx4 v[118:119], off
	v_lshl_add_u64 v[28:29], v[114:115], 0, s[38:39]
	s_mov_b32 m0, s2
	s_mov_b64 s[2:3], 0x24000
	v_add_u32_e32 v0, 0x6000, v216
	global_load_lds_dwordx4 v[28:29], off
	v_lshl_add_u64 v[28:29], v[114:115], 0, s[2:3]
	v_readfirstlane_b32 s2, v0
	s_mov_b32 m0, s2
	s_mov_b64 s[2:3], 0x18080
	v_add_u32_e32 v0, 0x7000, v216
	global_load_lds_dwordx4 v[28:29], off
	v_lshl_add_u64 v[28:29], v[116:117], 0, s[2:3]
	v_readfirstlane_b32 s2, v0
	v_add_u32_e32 v0, 0x8000, v216
	s_mov_b32 m0, s2
	v_readfirstlane_b32 s2, v0
	v_add_u32_e32 v0, 0x9000, v216
	global_load_lds_dwordx4 v[28:29], off
	v_lshl_add_u64 v[28:29], v[112:113], 0, s[40:41]
	s_mov_b32 m0, s2
	v_readfirstlane_b32 s2, v0
	global_load_lds_dwordx4 v[28:29], off
	v_lshl_add_u64 v[28:29], v[118:119], 0, s[40:41]
	s_mov_b32 m0, s2
	v_add_u32_e32 v0, 0xa000, v216
	global_load_lds_dwordx4 v[28:29], off
	v_readfirstlane_b32 s2, v0
	s_waitcnt vmcnt(5)
	v_lshl_add_u64 v[28:29], v[114:115], 0, s[4:5]
	s_mov_b32 m0, s2
	s_mov_b64 s[2:3], 0x3c000
	v_add_u32_e32 v0, 0xb000, v216
	s_waitcnt lgkmcnt(0)
	s_barrier
	global_load_lds_dwordx4 v[28:29], off
	v_lshl_add_u64 v[28:29], v[114:115], 0, s[2:3]
	v_readfirstlane_b32 s2, v0
	s_mov_b32 m0, s2
	s_mov_b64 s[2:3], 0x30080
	v_add_u32_e32 v0, 0xc000, v216
	global_load_lds_dwordx4 v[28:29], off
	v_lshl_add_u64 v[28:29], v[116:117], 0, s[2:3]
	v_readfirstlane_b32 s2, v0
	v_add_u32_e32 v0, 0xd000, v216
	s_mov_b32 m0, s2
	s_mov_b64 s[8:9], 0x100
	v_readfirstlane_b32 s2, v0
	v_add_u32_e32 v0, 0xe000, v216
	global_load_lds_dwordx4 v[28:29], off
	v_lshl_add_u64 v[28:29], v[112:113], 0, s[8:9]
	s_mov_b32 m0, s2
	v_readfirstlane_b32 s2, v0
	global_load_lds_dwordx4 v[28:29], off
	v_lshl_add_u64 v[28:29], v[118:119], 0, s[8:9]
	s_mov_b32 m0, s2
	s_mov_b64 s[28:29], 0x80
	global_load_lds_dwordx4 v[28:29], off
	v_cmp_le_i32_e32 vcc, s57, v208
	s_and_saveexec_b64 s[2:3], vcc
	s_xor_b64 s[2:3], exec, s[2:3]
	s_or_saveexec_b64 s[2:3], s[2:3]
	v_lshrrev_b32_e32 v0, 4, v2
	v_bfe_u32 v3, v2, 1, 3
	v_lshrrev_b32_e32 v2, 2, v2
	v_lshlrev_b32_e32 v28, 1, v3
	v_lshlrev_b32_e32 v29, 7, v186
	v_bitop3_b32 v30, v0, v3, 3 bitop3:0x6c
	v_bitop3_b32 v3, v187, v3, 4 bitop3:0x36
	v_sub_u32_e32 v2, 0, v2
	v_lshl_or_b32 v213, v30, 4, v29
	v_lshl_or_b32 v214, v3, 4, v29
	v_or_b32_e32 v3, 0x3000, v29
	v_bitop3_b32 v29, v28, v0, 3 bitop3:0x78
	v_xor_b32_e32 v0, v0, v2
	v_lshl_or_b32 v209, v29, 3, v3
	v_bitop3_b32 v29, v187, v28, 4 bitop3:0x36
	v_lshlrev_b32_e32 v0, 4, v0
	v_lshl_or_b32 v210, v29, 3, v3
	v_bitop3_b32 v29, v187, v28, 8 bitop3:0x36
	v_bitop3_b32 v28, v187, v28, 12 bitop3:0x36
	v_and_b32_e32 v0, 48, v0
	v_lshlrev_b32_e32 v2, 6, v186
	s_movk_i32 s8, 0x2000
	v_lshl_or_b32 v211, v29, 3, v3
	v_lshl_or_b32 v212, v28, 3, v3
	v_or3_b32 v215, v0, v2, s8
	v_mov_b32_e32 v2, v1
	v_mov_b32_e32 v3, v1
	v_mov_b32_e32 v0, v1
	v_mov_b64_e32 v[30:31], v[2:3]
	v_mov_b64_e32 v[34:35], v[2:3]
	v_mov_b64_e32 v[38:39], v[2:3]
	v_mov_b64_e32 v[42:43], v[2:3]
	v_mov_b64_e32 v[46:47], v[2:3]
	v_mov_b64_e32 v[50:51], v[2:3]
	v_mov_b64_e32 v[54:55], v[2:3]
	v_mov_b64_e32 v[58:59], v[2:3]
	s_mov_b32 s9, 0
	v_mov_b32_e32 v108, 0
	v_mov_b64_e32 v[28:29], v[0:1]
	v_mov_b64_e32 v[32:33], v[0:1]
	v_mov_b64_e32 v[36:37], v[0:1]
	v_mov_b64_e32 v[40:41], v[0:1]
	v_mov_b64_e32 v[44:45], v[0:1]
	v_mov_b64_e32 v[48:49], v[0:1]
	v_mov_b64_e32 v[52:53], v[0:1]
	v_mov_b64_e32 v[56:57], v[0:1]
	v_mov_b32_e32 v109, 0
	v_mov_b32_e32 v110, 0
	v_mov_b32_e32 v111, 0
	s_xor_b64 exec, exec, s[2:3]
	s_cbranch_execz .LBB0_2311
; template <int DK, int QB, bool NA>
; DEVI void attn_item(const AttnArgs& a, unsigned char* smem) {
;     ...
;         const unsigned a0 = cur + ka0, a1 = cur + ka1, a2 = cur + kr;
;         k0[0] = ldsr<0>(a0); k0[1] = ldsr<2048>(a0); k0[2] = ldsr<4096>(a0); k0[3] = ldsr<6144>(a0);
;         k1[0] = ldsr<0>(a1); k1[1] = ldsr<2048>(a1); k1[2] = ldsr<4096>(a1); k1[3] = ldsr<6144>(a1);
;         if constexpr (KS == 3) { k2[0] = ldsr<0>(a2); k2[1] = ldsr<1024>(a2); k2[2] = ldsr<2048>(a2); k2[3] = ldsr<3072>(a2); }
;         if constexpr (KS == 3) asm volatile("s_waitcnt lgkmcnt(8)" : "+v"(k0[0]), "+v"(k0[1]), "+v"(k0[2]), "+v"(k0[3]) :: "memory");
;         else                   asm volatile("s_waitcnt lgkmcnt(4)" : "+v"(k0[0]), "+v"(k0[1]), "+v"(k0[2]), "+v"(k0[3]) :: "memory");
;         __builtin_amdgcn_sched_barrier(0);
; #pragma unroll
;         for (int kb = 0; kb < 4; ++kb)
; #pragma unroll
;           for (int qb = 0; qb < QB; ++qb) s[kb][qb] = __builtin_amdgcn_mfma_f32_16x16x32_bf16(k0[kb], qf[qb][0], s[kb][qb], 0, 0, 0);
;         if constexpr (KS == 3) asm volatile("s_waitcnt lgkmcnt(4)" : "+v"(k1[0]), "+v"(k1[1]), "+v"(k1[2]), "+v"(k1[3]) :: "memory");
;         else                   asm volatile("s_waitcnt lgkmcnt(0)" : "+v"(k1[0]), "+v"(k1[1]), "+v"(k1[2]), "+v"(k1[3]) :: "memory");
;         __builtin_amdgcn_sched_barrier(0);
; #pragma unroll
;         for (int kb = 0; kb < 4; ++kb)
; #pragma unroll
;           for (int qb = 0; qb < QB; ++qb) s[kb][qb] = __builtin_amdgcn_mfma_f32_16x16x32_bf16(k1[kb], qf[qb][1], s[kb][qb], 0, 0, 0);
;         if constexpr (KS == 3) {
;           asm volatile("s_waitcnt lgkmcnt(0)" : "+v"(k2[0]), "+v"(k2[1]), "+v"(k2[2]), "+v"(k2[3]) :: "memory");
;           __builtin_amdgcn_sched_barrier(0);
; #pragma unroll
;           for (int kb = 0; kb < 4; ++kb)
; #pragma unroll
;             for (int qb = 0; qb < QB; ++qb) s[kb][qb] = __builtin_amdgcn_mfma_f32_16x16x32_bf16(k2[kb], qf[qb][2], s[kb][qb], 0, 0, 0);
;         }
;       }
;     ...
;           const f32x2 scv = {a.sc2, a.sc2}, nmv = {-m[qb], -m[qb]};
;           f32x2 t[4][2];
; #pragma unroll
;           for (int kb = 0; kb < 4; ++kb)
; #pragma unroll
;             for (int h = 0; h < 2; ++h) {
;               const f32x2 sv = {s[kb][qb][2 * h], s[kb][qb][2 * h + 1]};
;               t[kb][h] = sv * scv + nmv;
;             }
	ds_read_b128 v[28:31], v213 offset:0
	ds_read_b128 v[32:35], v213 offset:0x800
	ds_read_b128 v[36:39], v213 offset:0x1000
	ds_read_b128 v[40:43], v213 offset:0x1800
	ds_read_b128 v[44:47], v214 offset:0
	ds_read_b128 v[48:51], v214 offset:0x800
	ds_read_b128 v[52:55], v214 offset:0x1000
	ds_read_b128 v[56:59], v214 offset:0x1800
	ds_read_b128 v[60:63], v215 offset:0
	ds_read_b128 v[64:67], v215 offset:0x400
	ds_read_b128 v[76:79], v215 offset:0x800
	ds_read_b128 v[80:83], v215 offset:0xc00
	s_nop 0
	s_waitcnt lgkmcnt(8)
	s_waitcnt vmcnt(0)
	s_setprio 1
	v_mfma_f32_16x16x32_bf16 v[68:71], v[28:31], v[24:27], 0
	s_waitcnt lgkmcnt(4)
	v_mfma_f32_16x16x32_bf16 v[28:31], v[28:31], v[20:23], 0
	v_mfma_f32_16x16x32_bf16 v[72:75], v[32:35], v[24:27], 0
	v_mfma_f32_16x16x32_bf16 v[32:35], v[32:35], v[20:23], 0
	v_mfma_f32_16x16x32_bf16 v[84:87], v[36:39], v[24:27], 0
	v_mfma_f32_16x16x32_bf16 v[36:39], v[36:39], v[20:23], 0
	v_mfma_f32_16x16x32_bf16 v[88:91], v[40:43], v[24:27], 0
	v_mfma_f32_16x16x32_bf16 v[40:43], v[40:43], v[20:23], 0
	v_mfma_f32_16x16x32_bf16 v[68:71], v[44:47], v[16:19], v[68:71]
	s_waitcnt lgkmcnt(0)
	v_mfma_f32_16x16x32_bf16 v[28:31], v[44:47], v[12:15], v[28:31]
	v_mfma_f32_16x16x32_bf16 v[44:47], v[48:51], v[16:19], v[72:75]
	v_mfma_f32_16x16x32_bf16 v[32:35], v[48:51], v[12:15], v[32:35]
	v_mfma_f32_16x16x32_bf16 v[48:51], v[52:55], v[16:19], v[84:87]
	v_mfma_f32_16x16x32_bf16 v[36:39], v[52:55], v[12:15], v[36:39]
	v_mfma_f32_16x16x32_bf16 v[52:55], v[56:59], v[16:19], v[88:91]
	v_mfma_f32_16x16x32_bf16 v[40:43], v[56:59], v[12:15], v[40:43]
	v_mfma_f32_16x16x32_bf16 v[84:87], v[60:63], v[8:11], v[68:71]
	ds_read_b64 v[56:57], v209 offset:0
	ds_read_b64 v[58:59], v210 offset:0
	v_mfma_f32_16x16x32_bf16 v[68:71], v[60:63], v[4:7], v[28:31]
	v_mfma_f32_16x16x32_bf16 v[60:63], v[64:67], v[8:11], v[44:47]
	s_nop 5
	v_mul_f32_e64 v92, v86, s34
	v_mul_f32_e64 v93, v87, s34
	v_pk_mul_f32 v[2:3], v[84:85], s[34:35] op_sel_hi:[1,0]
	v_max_f32_e32 v0, v92, v93
	v_mfma_f32_16x16x32_bf16 v[72:75], v[64:67], v[4:7], v[32:35]
	v_max3_f32 v0, v2, v3, v0
	v_pk_mul_f32 v[2:3], v[60:61], s[34:35] op_sel_hi:[1,0]
	v_mfma_f32_16x16x32_bf16 v[64:67], v[76:79], v[8:11], v[48:51]
	v_max_f32_e32 v92, v2, v3
	v_pk_mul_f32 v[2:3], v[62:63], s[34:35] op_sel_hi:[1,0]
	v_mfma_f32_16x16x32_bf16 v[88:91], v[80:83], v[8:11], v[52:55]
	v_max_f32_e32 v2, v2, v3
	v_max3_f32 v0, v0, v92, v2
	s_nop 2
	v_pk_mul_f32 v[2:3], v[64:65], s[34:35] op_sel_hi:[1,0]
	v_mfma_f32_16x16x32_bf16 v[76:79], v[76:79], v[4:7], v[36:39]
	v_max_f32_e32 v92, v2, v3
	v_pk_mul_f32 v[2:3], v[66:67], s[34:35] op_sel_hi:[1,0]
	ds_read_b64 v[52:53], v209 offset:0x800
	v_mfma_f32_16x16x32_bf16 v[80:83], v[80:83], v[4:7], v[40:43]
	s_setprio 0
	v_max_f32_e32 v2, v2, v3
	v_max3_f32 v0, v0, v92, v2
	v_pk_mul_f32 v[2:3], v[88:89], s[34:35] op_sel_hi:[1,0]
	ds_read_b64 v[54:55], v210 offset:0x800
	ds_read_b64 v[48:49], v209 offset:0x1000
	ds_read_b64 v[50:51], v210 offset:0x1000
	ds_read_b64 v[44:45], v209 offset:0x1800
	ds_read_b64 v[46:47], v210 offset:0x1800
	s_nop 0
	v_max_f32_e32 v92, v2, v3
	v_pk_mul_f32 v[2:3], v[90:91], s[34:35] op_sel_hi:[1,0]
	ds_read_b64 v[40:41], v211 offset:0
	ds_read_b64 v[42:43], v212 offset:0
	ds_read_b64 v[36:37], v211 offset:0x800
	ds_read_b64 v[38:39], v212 offset:0x800
	ds_read_b64 v[32:33], v211 offset:0x1000
	s_nop 0
	v_max_f32_e32 v2, v2, v3
	v_max3_f32 v0, v0, v92, v2
	v_mov_b32_e32 v2, v0
	s_nop 1
	v_permlane16_swap_b32_e32 v0, v2
	v_max_f32_e32 v2, v2, v2
	v_max_f32_e32 v0, v0, v0
	v_max_f32_e32 v0, v0, v2
	v_mov_b32_e32 v2, v0
	s_nop 1
	v_permlane32_swap_b32_e32 v0, v2
	v_max_f32_e32 v2, v2, v2
	v_max_f32_e32 v0, v0, v0
	v_max_f32_e32 v92, v0, v2
	v_fma_f32 v94, v62, s34, -v92
	v_fma_f32 v95, v63, s34, -v92
	v_fma_f32 v62, v60, s34, -v92
	v_fma_f32 v63, v61, s34, -v92
	v_fma_f32 v60, v84, s34, -v92
	v_fma_f32 v61, v85, s34, -v92
	v_fma_f32 v86, v86, s34, -v92
	v_fma_f32 v87, v87, s34, -v92
	v_exp_f32_e32 v60, v60
	v_exp_f32_e32 v61, v61
	v_exp_f32_e32 v86, v86
	v_exp_f32_e32 v87, v87
	v_exp_f32_e32 v62, v62
	v_pk_add_f32 v[84:85], v[60:61], 0 op_sel_hi:[1,0]
	v_exp_f32_e32 v63, v63
	v_fma_f32 v64, v64, s34, -v92
	v_fma_f32 v65, v65, s34, -v92
	v_cvt_pk_bf16_f32 v60, v60, v61
	v_pk_add_f32 v[84:85], v[86:87], v[84:85]
	v_cvt_pk_bf16_f32 v61, v86, v87
	v_exp_f32_e32 v86, v94
	v_exp_f32_e32 v87, v95
	v_fma_f32 v66, v66, s34, -v92
	v_fma_f32 v67, v67, s34, -v92
	v_exp_f32_e32 v64, v64
	v_exp_f32_e32 v65, v65
	v_exp_f32_e32 v66, v66
	v_exp_f32_e32 v67, v67
	v_pk_add_f32 v[84:85], v[62:63], v[84:85]
	v_fma_f32 v88, v88, s34, -v92
	v_fma_f32 v89, v89, s34, -v92
	v_pk_add_f32 v[84:85], v[86:87], v[84:85]
	v_fma_f32 v90, v90, s34, -v92
	v_fma_f32 v91, v91, s34, -v92
	v_pk_add_f32 v[84:85], v[64:65], v[84:85]
	v_cvt_pk_bf16_f32 v64, v64, v65
	v_pk_add_f32 v[84:85], v[66:67], v[84:85]
	v_cvt_pk_bf16_f32 v65, v66, v67
	v_exp_f32_e32 v66, v88
	v_exp_f32_e32 v67, v89
	v_cvt_pk_bf16_f32 v62, v62, v63
	v_cvt_pk_bf16_f32 v63, v86, v87
	v_exp_f32_e32 v86, v90
	v_exp_f32_e32 v87, v91
	v_pk_add_f32 v[84:85], v[66:67], v[84:85]
	v_pk_mul_f32 v[88:89], v[70:71], s[34:35] op_sel_hi:[1,0]
	v_cvt_pk_bf16_f32 v66, v66, v67
	v_pk_add_f32 v[84:85], v[86:87], v[84:85]
	v_cvt_pk_bf16_f32 v67, v86, v87
	v_pk_mul_f32 v[86:87], v[68:69], s[34:35] op_sel_hi:[1,0]
	v_max_f32_e32 v0, v88, v89
	v_max3_f32 v0, v86, v87, v0
	v_pk_mul_f32 v[86:87], v[72:73], s[34:35] op_sel_hi:[1,0]
	v_exp_f32_e64 v3, -v92
	v_max_f32_e32 v2, v86, v87
	v_pk_mul_f32 v[86:87], v[74:75], s[34:35] op_sel_hi:[1,0]
	ds_read_b64 v[34:35], v212 offset:0x1000
	ds_read_b64 v[28:29], v211 offset:0x1800
	ds_read_b64 v[30:31], v212 offset:0x1800
	s_nop 0
	v_max_f32_e32 v86, v86, v87
	v_max3_f32 v0, v0, v2, v86
	v_pk_mul_f32 v[86:87], v[76:77], s[34:35] op_sel_hi:[1,0]
	s_waitcnt lgkmcnt(0)
; template <int DK, int QB, bool NA>
; DEVI void attn_item(const AttnArgs& a, unsigned char* smem) {
;     ...
;           const f32x2 scv = {a.sc2, a.sc2}, nmv = {-m[qb], -m[qb]};
;           f32x2 t[4][2];
; #pragma unroll
;           for (int kb = 0; kb < 4; ++kb)
; #pragma unroll
;             for (int h = 0; h < 2; ++h) {
;               const f32x2 sv = {s[kb][qb][2 * h], s[kb][qb][2 * h + 1]};
;               t[kb][h] = sv * scv + nmv;
;             }
;           float mx = fmaxf(t[0][0].x, t[0][0].y);
; #pragma unroll
;           for (int kb = 0; kb < 4; ++kb)
; #pragma unroll
;             for (int h = 0; h < 2; ++h) mx = fmaxf(mx, fmaxf(t[kb][h].x, t[kb][h].y));
;           if (j == 0 || __any(mx > 6.f)) {
;             mx = xmax32(xmax16(mx));
;             const float d = (j == 0) ? mx : fmaxf(mx, 0.f);
;             const float alpha = __builtin_amdgcn_exp2f(-d);
;             const f32x2 dv = {d, d};
; #pragma unroll
;             for (int kb = 0; kb < 4; ++kb)
; #pragma unroll
;               for (int h = 0; h < 2; ++h) t[kb][h] -= dv;
;             m[qb] += d;
;             l[qb] *= alpha;
; #pragma unroll
;             for (int db = 0; db < 4; ++db) o[db][qb] *= alpha;
;           }
;           f32x2 ls2 = {0.f, 0.f};
;           unsigned pw[2][4];
; #pragma unroll
;           for (int kb = 0; kb < 4; ++kb)
; #pragma unroll
;             for (int h = 0; h < 2; ++h) {
;               const f32x2 pe = {__builtin_amdgcn_exp2f(t[kb][h].x), __builtin_amdgcn_exp2f(t[kb][h].y)};
;               ls2 += pe;
;               pw[kb >> 1][(kb & 1) * 2 + h] = pk2(pe.x, pe.y);
;             }
;           l[qb] += ls2.x + ls2.y;
; #pragma unroll
;           for (int c = 0; c < 2; ++c) {
;             const u32x4 pv = (u32x4){pw[c][0], pw[c][1], pw[c][2], pw[c][3]};
;             pf[qb][c] = __builtin_bit_cast(bf16x8, pv);
;           }
;         }
;     ...
;       asm volatile("s_waitcnt lgkmcnt(0)"
;                    : "+v"(va[0][0]), "+v"(va[0][1]), "+v"(va[0][2]), "+v"(va[0][3]), "+v"(va[1][0]), "+v"(va[1][1]), "+v"(va[1][2]), "+v"(va[1][3]),
;                      "+v"(vbq[0][0]), "+v"(vbq[0][1]), "+v"(vbq[0][2]), "+v"(vbq[0][3]), "+v"(vbq[1][0]), "+v"(vbq[1][1]), "+v"(vbq[1][2]), "+v"(vbq[1][3])
;                    :: "memory");
;       __builtin_amdgcn_sched_barrier(0);
; #pragma unroll
;       for (int c = 0; c < 2; ++c)
; #pragma unroll
	s_nop 0
	v_max_f32_e32 v2, v86, v87
	v_pk_mul_f32 v[86:87], v[78:79], s[34:35] op_sel_hi:[1,0]
	s_nop 0
	v_max_f32_e32 v86, v86, v87
	v_max3_f32 v0, v0, v2, v86
	v_pk_mul_f32 v[86:87], v[80:81], s[34:35] op_sel_hi:[1,0]
	s_nop 0
	v_max_f32_e32 v2, v86, v87
	v_pk_mul_f32 v[86:87], v[82:83], s[34:35] op_sel_hi:[1,0]
	s_nop 0
	v_max_f32_e32 v86, v86, v87
	v_max3_f32 v0, v0, v2, v86
	v_mov_b32_e32 v2, v0
	s_nop 1
	v_permlane16_swap_b32_e32 v0, v2
	v_max_f32_e32 v2, v2, v2
	v_max_f32_e32 v0, v0, v0
	v_max_f32_e32 v0, v0, v2
	v_mov_b32_e32 v2, v0
	s_nop 1
	v_permlane32_swap_b32_e32 v0, v2
	v_max_f32_e32 v2, v2, v2
	v_max_f32_e32 v0, v0, v0
	v_max_f32_e32 v93, v0, v2
	v_mov_b32_e32 v0, v93
	v_fma_f32 v68, v68, s34, -v0
	v_fma_f32 v69, v69, s34, -v0
	v_fma_f32 v70, v70, s34, -v0
	v_fma_f32 v71, v71, s34, -v0
	v_exp_f32_e32 v68, v68
	v_exp_f32_e32 v69, v69
	v_exp_f32_e32 v70, v70
	v_exp_f32_e32 v71, v71
	v_fma_f32 v72, v72, s34, -v0
	v_fma_f32 v73, v73, s34, -v0
	v_pk_add_f32 v[86:87], v[68:69], 0 op_sel_hi:[1,0]
	v_fma_f32 v74, v74, s34, -v0
	v_fma_f32 v75, v75, s34, -v0
	v_cvt_pk_bf16_f32 v68, v68, v69
	v_pk_add_f32 v[86:87], v[70:71], v[86:87]
	v_cvt_pk_bf16_f32 v69, v70, v71
	v_exp_f32_e32 v70, v72
	v_exp_f32_e32 v71, v73
	v_exp_f32_e32 v74, v74
	v_exp_f32_e32 v75, v75
	v_fma_f32 v76, v76, s34, -v0
	v_fma_f32 v77, v77, s34, -v0
	v_pk_add_f32 v[72:73], v[70:71], v[86:87]
	v_cvt_pk_bf16_f32 v70, v70, v71
	v_pk_add_f32 v[72:73], v[74:75], v[72:73]
	v_cvt_pk_bf16_f32 v71, v74, v75
	v_exp_f32_e32 v74, v76
	v_exp_f32_e32 v75, v77
	v_fma_f32 v78, v78, s34, -v0
	v_fma_f32 v79, v79, s34, -v0
	v_fma_f32 v80, v80, s34, -v0
	v_fma_f32 v81, v81, s34, -v0
	v_fma_f32 v82, v82, s34, -v0
	v_fma_f32 v83, v83, s34, -v0
	v_pk_add_f32 v[76:77], v[74:75], v[72:73]
	v_cvt_pk_bf16_f32 v72, v74, v75
	v_exp_f32_e32 v74, v78
	v_exp_f32_e32 v75, v79
	v_exp_f32_e32 v78, v82
	v_exp_f32_e32 v79, v83
	v_exp_f32_e64 v2, -v93
	v_pk_add_f32 v[76:77], v[74:75], v[76:77]
	v_cvt_pk_bf16_f32 v73, v74, v75
	v_exp_f32_e32 v74, v80
	v_exp_f32_e32 v75, v81
	v_pk_add_f32 v[110:111], v[92:93], 0 op_sel_hi:[1,0]
	v_pk_add_f32 v[76:77], v[74:75], v[76:77]
	s_nop 0
	v_pk_add_f32 v[86:87], v[78:79], v[76:77]
	v_cvt_pk_bf16_f32 v74, v74, v75
	v_cvt_pk_bf16_f32 v75, v78, v79
	v_mov_b32_e32 v78, v86
	v_mov_b32_e32 v79, v84
	v_mov_b32_e32 v84, v87
	v_pk_add_f32 v[84:85], v[78:79], v[84:85]
	v_pk_mul_f32 v[76:77], v[2:3], 0 op_sel_hi:[1,0]
	v_pk_fma_f32 v[108:109], v[2:3], 0, v[84:85] op_sel_hi:[1,0,1]
	v_mov_b32_e32 v80, v77
	v_mov_b32_e32 v81, v77
	v_mov_b32_e32 v82, v77
	v_mov_b32_e32 v83, v77
	v_mov_b32_e32 v77, v76
	v_mov_b32_e32 v78, v76
	v_mov_b32_e32 v79, v76
	s_setprio 1
	v_mfma_f32_16x16x32_bf16 v[84:87], v[56:59], v[60:63], v[80:83]
	s_nop 0
	v_mfma_f32_16x16x32_bf16 v[88:91], v[56:59], v[68:71], v[76:79]
	v_mfma_f32_16x16x32_bf16 v[92:95], v[52:55], v[60:63], v[80:83]
	v_mfma_f32_16x16x32_bf16 v[96:99], v[52:55], v[68:71], v[76:79]
	v_mfma_f32_16x16x32_bf16 v[100:103], v[48:51], v[60:63], v[80:83]
	v_mfma_f32_16x16x32_bf16 v[104:107], v[48:51], v[68:71], v[76:79]
	v_mfma_f32_16x16x32_bf16 v[60:63], v[44:47], v[60:63], v[80:83]
	v_mfma_f32_16x16x32_bf16 v[68:71], v[44:47], v[68:71], v[76:79]
	v_mfma_f32_16x16x32_bf16 v[56:59], v[40:43], v[64:67], v[84:87]
	v_mfma_f32_16x16x32_bf16 v[52:55], v[40:43], v[72:75], v[88:91]
	v_mfma_f32_16x16x32_bf16 v[48:51], v[36:39], v[64:67], v[92:95]
	v_mfma_f32_16x16x32_bf16 v[44:47], v[36:39], v[72:75], v[96:99]
	v_mfma_f32_16x16x32_bf16 v[40:43], v[32:35], v[64:67], v[100:103]
	v_mfma_f32_16x16x32_bf16 v[36:39], v[32:35], v[72:75], v[104:107]
	v_mfma_f32_16x16x32_bf16 v[32:35], v[28:31], v[64:67], v[60:63]
	v_mfma_f32_16x16x32_bf16 v[28:31], v[28:31], v[72:75], v[68:71]
	s_setprio 0

; template <int DK, int QB, bool NA>
; DEVI void attn_item(const AttnArgs& a, unsigned char* smem) {
;     ...
;   for (int j = 0; j < nt; ++j) {
;     if (j + 1 < nt) {
;       if constexpr (DK == 96) asm volatile("s_waitcnt vmcnt(5)" ::: "memory");
;       else                    asm volatile("s_waitcnt vmcnt(4)" ::: "memory");
;     } else {
;       asm volatile("s_waitcnt vmcnt(0)" ::: "memory");
;     }
;     RAW_BARRIER();
;     if (j + 2 < nt) ATT_ISSUE(j + 2, is);
;     is = (is + 1 == S) ? 0 : is + 1;
;     const unsigned cur = lbase + cs * ATT_STAGE;
;     cs = (cs + 1 == S) ? 0 : cs + 1;
;     if (wact) {
;       f32x4 s[4][QB];
; #pragma unroll
;       for (int kb = 0; kb < 4; ++kb)
; #pragma unroll
;         for (int qb = 0; qb < QB; ++qb) s[kb][qb] = (f32x4){0.f, 0.f, 0.f, 0.f};
;       {
;         bf16x8 k0[4], k1[4], k2[4];
;         const unsigned a0 = cur + ka0, a1 = cur + ka1, a2 = cur + kr;
;         k0[0] = ldsr<0>(a0); k0[1] = ldsr<2048>(a0); k0[2] = ldsr<4096>(a0); k0[3] = ldsr<6144>(a0);
;         k1[0] = ldsr<0>(a1); k1[1] = ldsr<2048>(a1); k1[2] = ldsr<4096>(a1); k1[3] = ldsr<6144>(a1);
;         if constexpr (KS == 3) { k2[0] = ldsr<0>(a2); k2[1] = ldsr<1024>(a2); k2[2] = ldsr<2048>(a2); k2[3] = ldsr<3072>(a2); }
;         if constexpr (KS == 3) asm volatile("s_waitcnt lgkmcnt(8)" : "+v"(k0[0]), "+v"(k0[1]), "+v"(k0[2]), "+v"(k0[3]) :: "memory");
;         else                   asm volatile("s_waitcnt lgkmcnt(4)" : "+v"(k0[0]), "+v"(k0[1]), "+v"(k0[2]), "+v"(k0[3]) :: "memory");
;         __builtin_amdgcn_sched_barrier(0);
; #pragma unroll
;         for (int kb = 0; kb < 4; ++kb)
; #pragma unroll
;           for (int qb = 0; qb < QB; ++qb) s[kb][qb] = __builtin_amdgcn_mfma_f32_16x16x32_bf16(k0[kb], qf[qb][0], s[kb][qb], 0, 0, 0);
;         if constexpr (KS == 3) asm volatile("s_waitcnt lgkmcnt(4)" : "+v"(k1[0]), "+v"(k1[1]), "+v"(k1[2]), "+v"(k1[3]) :: "memory");
;         else                   asm volatile("s_waitcnt lgkmcnt(0)" : "+v"(k1[0]), "+v"(k1[1]), "+v"(k1[2]), "+v"(k1[3]) :: "memory");
;         __builtin_amdgcn_sched_barrier(0);
; #pragma unroll
;         for (int kb = 0; kb < 4; ++kb)
; #pragma unroll
;           for (int qb = 0; qb < QB; ++qb) s[kb][qb] = __builtin_amdgcn_mfma_f32_16x16x32_bf16(k1[kb], qf[qb][1], s[kb][qb], 0, 0, 0);
;         if constexpr (KS == 3) {
.LBB0_2314:
	s_add_i32 s42, s42, 1
	s_cmp_lt_u32 s42, s61
	s_cselect_b32 s20, s43, s60
	s_mul_i32 s2, s9, 0x5000
	v_add_u32_e32 v0, s2, v216
	v_mad_u64_u32 v[2:3], s[2:3], s20, v207, v[114:115]
	v_readfirstlane_b32 s2, v0
	v_add_u32_e32 v221, 0x1000, v0
	s_mul_i32 s100, s8, 0x5000
	v_or_b32_e32 v218, s100, v213
	v_or_b32_e32 v219, s100, v214
	v_add_u32_e32 v220, s100, v215
	s_waitcnt vmcnt(5)
	s_mov_b32 m0, s2
	v_readfirstlane_b32 s101, v221
	s_waitcnt lgkmcnt(0)
	s_barrier
	ds_read_b128 v[60:63], v218 offset:0
	ds_read_b128 v[64:67], v218 offset:0x800
	ds_read_b128 v[68:71], v218 offset:0x1000
	ds_read_b128 v[72:75], v218 offset:0x1800
	ds_read_b128 v[76:79], v219 offset:0
	ds_read_b128 v[80:83], v219 offset:0x800
	ds_read_b128 v[84:87], v219 offset:0x1000
	ds_read_b128 v[88:91], v219 offset:0x1800
	ds_read_b128 v[92:95], v220 offset:0
	ds_read_b128 v[96:99], v220 offset:0x400
	ds_read_b128 v[120:123], v220 offset:0x800
	ds_read_b128 v[124:127], v220 offset:0xc00
	s_and_saveexec_b64 s[2:3], s[0:1]
	s_cbranch_execz .Lml_dma_stub
	s_waitcnt lgkmcnt(8)
	s_setprio 1
	v_mfma_f32_16x16x32_bf16 v[100:103], v[60:63], v[24:27], 0
	global_load_lds_dwordx4 v[2:3], off
	v_lshl_add_u64 v[2:3], v[2:3], 0, s[86:87]
	s_mov_b32 m0, s101
	s_waitcnt lgkmcnt(4)
	v_mfma_f32_16x16x32_bf16 v[60:63], v[60:63], v[20:23], 0
	v_add_u32_e32 v221, 0x2000, v0
	global_load_lds_dwordx4 v[2:3], off
	v_mfma_f32_16x16x32_bf16 v[104:107], v[64:67], v[24:27], 0
	v_mad_u64_u32 v[2:3], vcc, s20, v207, v[116:117]
	v_readfirstlane_b32 s101, v221
	v_add_u32_e32 v221, 0x3000, v0
	v_mfma_f32_16x16x32_bf16 v[64:67], v[64:67], v[20:23], 0
	v_lshl_add_u64 v[2:3], v[2:3], 0, s[28:29]
	s_mov_b32 m0, s101
	s_lshl_b64 vcc, s[20:21], 1
	v_mfma_f32_16x16x32_bf16 v[180:183], v[68:71], v[24:27], 0
	v_readfirstlane_b32 s20, v221
	global_load_lds_dwordx4 v[2:3], off
	v_lshl_add_u64 v[2:3], v[112:113], 0, vcc
	v_mfma_f32_16x16x32_bf16 v[68:71], v[68:71], v[20:23], 0
	s_mov_b32 m0, s20
	v_add_u32_e32 v0, 0x4000, v0
	global_load_lds_dwordx4 v[2:3], off
	v_mfma_f32_16x16x32_bf16 v[218:221], v[72:75], v[24:27], 0
	v_lshl_add_u64 v[2:3], v[118:119], 0, vcc
	v_readfirstlane_b32 s101, v0
	s_mov_b32 m0, s101
	v_mfma_f32_16x16x32_bf16 v[72:75], v[72:75], v[20:23], 0
	global_load_lds_dwordx4 v[2:3], off
	v_mfma_f32_16x16x32_bf16 v[100:103], v[76:79], v[16:19], v[100:103]
	s_waitcnt lgkmcnt(0)
	v_mfma_f32_16x16x32_bf16 v[60:63], v[76:79], v[12:15], v[60:63]
	v_mfma_f32_16x16x32_bf16 v[76:79], v[80:83], v[16:19], v[104:107]
	v_mfma_f32_16x16x32_bf16 v[64:67], v[80:83], v[12:15], v[64:67]
	v_mfma_f32_16x16x32_bf16 v[80:83], v[84:87], v[16:19], v[180:183]
	v_mfma_f32_16x16x32_bf16 v[68:71], v[84:87], v[12:15], v[68:71]
	v_mfma_f32_16x16x32_bf16 v[84:87], v[88:91], v[16:19], v[218:221]
	v_mfma_f32_16x16x32_bf16 v[72:75], v[88:91], v[12:15], v[72:75]
	v_mfma_f32_16x16x32_bf16 v[182:185], v[92:95], v[8:11], v[100:103]
	v_add_u32_e32 v0, s100, v209
	v_add_u32_e32 v2, s100, v210
	ds_read_b64 v[88:89], v0 offset:0
	v_mfma_f32_16x16x32_bf16 v[218:221], v[96:99], v[8:11], v[76:79]
	ds_read_b64 v[90:91], v2 offset:0
	s_nop 4
	v_fma_f32 v180, v184, s34, -v110
	v_fma_f32 v181, v185, s34, -v110
	v_fma_f32 v182, v182, s34, -v110
	v_fma_f32 v183, v183, s34, -v110
	v_mfma_f32_16x16x32_bf16 v[222:225], v[120:123], v[8:11], v[80:83]
	v_add_u32_e32 v3, s100, v211
	v_fma_f32 v128, v220, s34, -v110
	v_fma_f32 v129, v221, s34, -v110
	v_mfma_f32_16x16x32_bf16 v[226:229], v[124:127], v[8:11], v[84:87]
	ds_read_b64 v[84:85], v0 offset:0x800
	ds_read_b64 v[86:87], v2 offset:0x800
	ds_read_b64 v[80:81], v0 offset:0x1000
	v_mfma_f32_16x16x32_bf16 v[104:107], v[92:95], v[4:7], v[60:63]
	ds_read_b64 v[82:83], v2 offset:0x1000
	ds_read_b64 v[76:77], v0 offset:0x1800
	v_max_f32_e32 v0, v180, v181
	v_mfma_f32_16x16x32_bf16 v[92:95], v[124:127], v[4:7], v[72:75]
	v_fma_f32 v126, v218, s34, -v110
	v_fma_f32 v127, v219, s34, -v110
	v_fma_f32 v124, v222, s34, -v110
	v_fma_f32 v125, v223, s34, -v110
	v_max3_f32 v0, v182, v183, v0
	v_mfma_f32_16x16x32_bf16 v[100:103], v[96:99], v[4:7], v[64:67]
	v_max_f32_e32 v184, v126, v127
	v_max_f32_e32 v185, v128, v129
	v_add_u32_e32 v62, s100, v212
	v_mfma_f32_16x16x32_bf16 v[96:99], v[120:123], v[4:7], v[68:71]
	s_setprio 0
	v_fma_f32 v122, v224, s34, -v110
	v_fma_f32 v123, v225, s34, -v110
	ds_read_b64 v[78:79], v2 offset:0x1800
	ds_read_b64 v[72:73], v3 offset:0
	ds_read_b64 v[74:75], v62 offset:0
	ds_read_b64 v[68:69], v3 offset:0x800
	ds_read_b64 v[70:71], v62 offset:0x800
	ds_read_b64 v[64:65], v3 offset:0x1000
	ds_read_b64 v[66:67], v62 offset:0x1000
	ds_read_b64 v[60:61], v3 offset:0x1800
	v_fma_f32 v120, v226, s34, -v110
	v_fma_f32 v121, v227, s34, -v110
	v_fma_f32 v2, v228, s34, -v110
	v_fma_f32 v3, v229, s34, -v110
	v_max3_f32 v0, v0, v184, v185
	v_max_f32_e32 v184, v124, v125
	v_max_f32_e32 v185, v122, v123
	v_max3_f32 v0, v0, v184, v185
	v_max_f32_e32 v184, v120, v121
	v_max_f32_e32 v185, v2, v3
	v_max3_f32 v0, v0, v184, v185
	s_mov_b32 s20, 0x40c00000
	v_cmp_lt_f32_e32 vcc, s20, v0
	ds_read_b64 v[62:63], v62 offset:0x1800
	s_cbranch_vccz .LBB0_2317
	v_mov_b32_e32 v184, v0
	s_nop 1
	v_permlane16_swap_b32_e32 v0, v184
	v_max_f32_e32 v184, v184, v184
	v_max_f32_e32 v0, v0, v0
	v_max_f32_e32 v0, v0, v184
	v_mov_b32_e32 v184, v0
	s_nop 1
	v_permlane32_swap_b32_e32 v0, v184
	v_max3_f32 v0, v0, v184, 0
	v_exp_f32_e64 v184, -v0
	v_pk_add_f32 v[182:183], v[182:183], v[0:1] op_sel_hi:[1,0] neg_lo:[0,1] neg_hi:[0,1]
	v_pk_add_f32 v[180:181], v[180:181], v[0:1] op_sel_hi:[1,0] neg_lo:[0,1] neg_hi:[0,1]
	v_pk_add_f32 v[126:127], v[126:127], v[0:1] op_sel_hi:[1,0] neg_lo:[0,1] neg_hi:[0,1]
	v_pk_add_f32 v[128:129], v[128:129], v[0:1] op_sel_hi:[1,0] neg_lo:[0,1] neg_hi:[0,1]
	v_pk_add_f32 v[124:125], v[124:125], v[0:1] op_sel_hi:[1,0] neg_lo:[0,1] neg_hi:[0,1]
	v_pk_add_f32 v[122:123], v[122:123], v[0:1] op_sel_hi:[1,0] neg_lo:[0,1] neg_hi:[0,1]
	v_pk_add_f32 v[120:121], v[120:121], v[0:1] op_sel_hi:[1,0] neg_lo:[0,1] neg_hi:[0,1]
	v_pk_add_f32 v[2:3], v[2:3], v[0:1] op_sel_hi:[1,0] neg_lo:[0,1] neg_hi:[0,1]
	v_add_f32_e32 v110, v110, v0
	v_mul_f32_e32 v109, v109, v184
	v_pk_mul_f32 v[58:59], v[58:59], v[184:185] op_sel_hi:[1,0]
	v_pk_mul_f32 v[56:57], v[56:57], v[184:185] op_sel_hi:[1,0]
	v_pk_mul_f32 v[50:51], v[50:51], v[184:185] op_sel_hi:[1,0]
	v_pk_mul_f32 v[48:49], v[48:49], v[184:185] op_sel_hi:[1,0]
	v_pk_mul_f32 v[42:43], v[42:43], v[184:185] op_sel_hi:[1,0]
	v_pk_mul_f32 v[40:41], v[40:41], v[184:185] op_sel_hi:[1,0]
	v_pk_mul_f32 v[34:35], v[34:35], v[184:185] op_sel_hi:[1,0]
	v_pk_mul_f32 v[32:33], v[32:33], v[184:185] op_sel_hi:[1,0]
; DEVI float xmax16(float x) { auto r = __builtin_amdgcn_permlane16_swap(__float_as_uint(x), __float_as_uint(x), false, false); return fmaxf(__uint_as_float(r[0]), __uint_as_float(r[1])); }
; DEVI float xmax32(float x) { auto r = __builtin_amdgcn_permlane32_swap(__float_as_uint(x), __float_as_uint(x), false, false); return fmaxf(__uint_as_float(r[0]), __uint_as_float(r[1])); }
; template <int DK, int QB, bool NA>
; DEVI void attn_item(const AttnArgs& a, unsigned char* smem) {
;     ...
;           const f32x2 scv = {a.sc2, a.sc2}, nmv = {-m[qb], -m[qb]};
;           f32x2 t[4][2];
; #pragma unroll
;           for (int kb = 0; kb < 4; ++kb)
; #pragma unroll
;             for (int h = 0; h < 2; ++h) {
;               const f32x2 sv = {s[kb][qb][2 * h], s[kb][qb][2 * h + 1]};
;               t[kb][h] = sv * scv + nmv;
;             }
;           float mx = fmaxf(t[0][0].x, t[0][0].y);
; #pragma unroll
;           for (int kb = 0; kb < 4; ++kb)
; #pragma unroll
;             for (int h = 0; h < 2; ++h) mx = fmaxf(mx, fmaxf(t[kb][h].x, t[kb][h].y));
;           if (j == 0 || __any(mx > 6.f)) {
;             mx = xmax32(xmax16(mx));
;             const float d = (j == 0) ? mx : fmaxf(mx, 0.f);
;             const float alpha = __builtin_amdgcn_exp2f(-d);
;             const f32x2 dv = {d, d};
; #pragma unroll
;             for (int kb = 0; kb < 4; ++kb)
; #pragma unroll
;               for (int h = 0; h < 2; ++h) t[kb][h] -= dv;
;             m[qb] += d;
;             l[qb] *= alpha;
; #pragma unroll
;             for (int db = 0; db < 4; ++db) o[db][qb] *= alpha;
;           }
.LBB0_2317:
	v_mov_b32_e32 v0, v111
	v_fma_f32 v106, v106, s34, -v0
	v_fma_f32 v107, v107, s34, -v0
	v_fma_f32 v184, v104, s34, -v0
	v_fma_f32 v185, v105, s34, -v0
	v_fma_f32 v104, v100, s34, -v0
	v_fma_f32 v105, v101, s34, -v0
	v_fma_f32 v102, v102, s34, -v0
	v_fma_f32 v103, v103, s34, -v0
	v_fma_f32 v100, v96, s34, -v0
	v_fma_f32 v101, v97, s34, -v0
	v_fma_f32 v98, v98, s34, -v0
	v_fma_f32 v99, v99, s34, -v0
	v_fma_f32 v96, v92, s34, -v0
	v_fma_f32 v97, v93, s34, -v0
	v_fma_f32 v92, v94, s34, -v0
	v_fma_f32 v93, v95, s34, -v0
	v_max_f32_e32 v0, v106, v107
	v_max3_f32 v0, v184, v185, v0
	v_max_f32_e32 v94, v104, v105
	v_max_f32_e32 v95, v102, v103
	v_max3_f32 v0, v0, v94, v95
	v_max_f32_e32 v94, v100, v101
	v_max_f32_e32 v95, v98, v99
	v_max3_f32 v0, v0, v94, v95
	v_max_f32_e32 v94, v96, v97
	v_max_f32_e32 v95, v92, v93
	v_max3_f32 v0, v0, v94, v95
	v_cmp_lt_f32_e32 vcc, s20, v0
	s_cbranch_vccz .LBB0_2312
	v_mov_b32_e32 v94, v0
	s_nop 1
	v_permlane16_swap_b32_e32 v0, v94
	v_max_f32_e32 v94, v94, v94
	v_max_f32_e32 v0, v0, v0
	v_max_f32_e32 v0, v0, v94
	v_mov_b32_e32 v94, v0
	s_nop 1
	v_permlane32_swap_b32_e32 v0, v94
	v_max3_f32 v0, v0, v94, 0
	v_exp_f32_e64 v94, -v0
	v_pk_add_f32 v[184:185], v[184:185], v[0:1] op_sel_hi:[1,0] neg_lo:[0,1] neg_hi:[0,1]
	v_pk_add_f32 v[106:107], v[106:107], v[0:1] op_sel_hi:[1,0] neg_lo:[0,1] neg_hi:[0,1]
	v_pk_add_f32 v[104:105], v[104:105], v[0:1] op_sel_hi:[1,0] neg_lo:[0,1] neg_hi:[0,1]
	v_pk_add_f32 v[102:103], v[102:103], v[0:1] op_sel_hi:[1,0] neg_lo:[0,1] neg_hi:[0,1]
	v_pk_add_f32 v[100:101], v[100:101], v[0:1] op_sel_hi:[1,0] neg_lo:[0,1] neg_hi:[0,1]
	v_pk_add_f32 v[98:99], v[98:99], v[0:1] op_sel_hi:[1,0] neg_lo:[0,1] neg_hi:[0,1]
	v_pk_add_f32 v[96:97], v[96:97], v[0:1] op_sel_hi:[1,0] neg_lo:[0,1] neg_hi:[0,1]
	v_pk_add_f32 v[92:93], v[92:93], v[0:1] op_sel_hi:[1,0] neg_lo:[0,1] neg_hi:[0,1]
	v_add_f32_e32 v111, v111, v0
	v_mul_f32_e32 v108, v108, v94
	v_pk_mul_f32 v[54:55], v[54:55], v[94:95] op_sel_hi:[1,0]
	v_pk_mul_f32 v[52:53], v[52:53], v[94:95] op_sel_hi:[1,0]
	v_pk_mul_f32 v[46:47], v[46:47], v[94:95] op_sel_hi:[1,0]
	v_pk_mul_f32 v[44:45], v[44:45], v[94:95] op_sel_hi:[1,0]
	v_pk_mul_f32 v[38:39], v[38:39], v[94:95] op_sel_hi:[1,0]
	v_pk_mul_f32 v[36:37], v[36:37], v[94:95] op_sel_hi:[1,0]
	v_pk_mul_f32 v[30:31], v[30:31], v[94:95] op_sel_hi:[1,0]
	v_pk_mul_f32 v[28:29], v[28:29], v[94:95] op_sel_hi:[1,0]
	s_branch .LBB0_2312

; template <int DK, int QB, bool NA>
; DEVI void attn_item(const AttnArgs& a, unsigned char* smem) {
;     ...
;     if (wact) {
;       f32x4 s[4][QB];
; #pragma unroll
;       for (int kb = 0; kb < 4; ++kb)
; #pragma unroll
;         for (int qb = 0; qb < QB; ++qb) s[kb][qb] = (f32x4){0.f, 0.f, 0.f, 0.f};
;       {
;         bf16x8 k0[4], k1[4], k2[4];
;         const unsigned a0 = cur + ka0, a1 = cur + ka1, a2 = cur + kr;
;         k0[0] = ldsr<0>(a0); k0[1] = ldsr<2048>(a0); k0[2] = ldsr<4096>(a0); k0[3] = ldsr<6144>(a0);
;         k1[0] = ldsr<0>(a1); k1[1] = ldsr<2048>(a1); k1[2] = ldsr<4096>(a1); k1[3] = ldsr<6144>(a1);
;         if constexpr (KS == 3) { k2[0] = ldsr<0>(a2); k2[1] = ldsr<1024>(a2); k2[2] = ldsr<2048>(a2); k2[3] = ldsr<3072>(a2); }
;         if constexpr (KS == 3) asm volatile("s_waitcnt lgkmcnt(8)" : "+v"(k0[0]), "+v"(k0[1]), "+v"(k0[2]), "+v"(k0[3]) :: "memory");
;         else                   asm volatile("s_waitcnt lgkmcnt(4)" : "+v"(k0[0]), "+v"(k0[1]), "+v"(k0[2]), "+v"(k0[3]) :: "memory");
;         __builtin_amdgcn_sched_barrier(0);
; #pragma unroll
;         for (int kb = 0; kb < 4; ++kb)
; #pragma unroll
;           for (int qb = 0; qb < QB; ++qb) s[kb][qb] = __builtin_amdgcn_mfma_f32_16x16x32_bf16(k0[kb], qf[qb][0], s[kb][qb], 0, 0, 0);
;         if constexpr (KS == 3) asm volatile("s_waitcnt lgkmcnt(4)" : "+v"(k1[0]), "+v"(k1[1]), "+v"(k1[2]), "+v"(k1[3]) :: "memory");
;         else                   asm volatile("s_waitcnt lgkmcnt(0)" : "+v"(k1[0]), "+v"(k1[1]), "+v"(k1[2]), "+v"(k1[3]) :: "memory");
;         __builtin_amdgcn_sched_barrier(0);
; #pragma unroll
;         for (int kb = 0; kb < 4; ++kb)
; #pragma unroll
;           for (int qb = 0; qb < QB; ++qb) s[kb][qb] = __builtin_amdgcn_mfma_f32_16x16x32_bf16(k1[kb], qf[qb][1], s[kb][qb], 0, 0, 0);
;         if constexpr (KS == 3) {
;           asm volatile("s_waitcnt lgkmcnt(0)" : "+v"(k2[0]), "+v"(k2[1]), "+v"(k2[2]), "+v"(k2[3]) :: "memory");
;           __builtin_amdgcn_sched_barrier(0);
; #pragma unroll
;           for (int kb = 0; kb < 4; ++kb)
; #pragma unroll
;             for (int qb = 0; qb < QB; ++qb) s[kb][qb] = __builtin_amdgcn_mfma_f32_16x16x32_bf16(k2[kb], qf[qb][2], s[kb][qb], 0, 0, 0);
;         }
;       }
;     ...
;           const f32x2 scv = {a.sc2, a.sc2}, nmv = {-m[qb], -m[qb]};
;           f32x2 t[4][2];
; #pragma unroll
.LBB0_2321:
	s_and_saveexec_b64 s[2:3], s[0:1]
	s_cbranch_execz .LBB0_2327
	s_mul_i32 s9, s8, 0x5000
	v_or_b32_e32 v0, s9, v213
	ds_read_b128 v[60:63], v0 offset:0
	ds_read_b128 v[64:67], v0 offset:0x800
	ds_read_b128 v[68:71], v0 offset:0x1000
	ds_read_b128 v[72:75], v0 offset:0x1800
	v_or_b32_e32 v2, s9, v214
	v_add_u32_e32 v3, s9, v215
	ds_read_b128 v[76:79], v2 offset:0
	ds_read_b128 v[80:83], v2 offset:0x800
	ds_read_b128 v[84:87], v2 offset:0x1000
	ds_read_b128 v[88:91], v2 offset:0x1800
	ds_read_b128 v[92:95], v3 offset:0
	ds_read_b128 v[96:99], v3 offset:0x400
	ds_read_b128 v[112:115], v3 offset:0x800
	ds_read_b128 v[116:119], v3 offset:0xc00
	s_waitcnt lgkmcnt(8)
	s_nop 0
	s_setprio 1
	v_mfma_f32_16x16x32_bf16 v[100:103], v[60:63], v[24:27], 0
	s_waitcnt lgkmcnt(4)
	v_mfma_f32_16x16x32_bf16 v[60:63], v[60:63], v[20:23], 0
	v_mfma_f32_16x16x32_bf16 v[104:107], v[64:67], v[24:27], 0
	v_mfma_f32_16x16x32_bf16 v[64:67], v[64:67], v[20:23], 0
	v_mfma_f32_16x16x32_bf16 v[120:123], v[68:71], v[24:27], 0
	v_mfma_f32_16x16x32_bf16 v[68:71], v[68:71], v[20:23], 0
	v_mfma_f32_16x16x32_bf16 v[124:127], v[72:75], v[24:27], 0
	v_mfma_f32_16x16x32_bf16 v[72:75], v[72:75], v[20:23], 0
	v_mfma_f32_16x16x32_bf16 v[100:103], v[76:79], v[16:19], v[100:103]
	s_waitcnt lgkmcnt(0)
	v_mfma_f32_16x16x32_bf16 v[60:63], v[76:79], v[12:15], v[60:63]
	v_mfma_f32_16x16x32_bf16 v[76:79], v[80:83], v[16:19], v[104:107]
	v_mfma_f32_16x16x32_bf16 v[64:67], v[80:83], v[12:15], v[64:67]
	v_mfma_f32_16x16x32_bf16 v[80:83], v[84:87], v[16:19], v[120:123]
	v_mfma_f32_16x16x32_bf16 v[68:71], v[84:87], v[12:15], v[68:71]
	v_mfma_f32_16x16x32_bf16 v[84:87], v[88:91], v[16:19], v[124:127]
	v_mfma_f32_16x16x32_bf16 v[72:75], v[88:91], v[12:15], v[72:75]
	v_mfma_f32_16x16x32_bf16 v[120:123], v[92:95], v[8:11], v[100:103]
	v_add_u32_e32 v0, s9, v209
	v_add_u32_e32 v2, s9, v210
	ds_read_b64 v[88:89], v0 offset:0
	v_mfma_f32_16x16x32_bf16 v[126:129], v[96:99], v[8:11], v[76:79]
	ds_read_b64 v[90:91], v2 offset:0
	s_nop 4
	v_fma_f32 v122, v122, s34, -v110
	v_fma_f32 v123, v123, s34, -v110
	v_fma_f32 v124, v120, s34, -v110
	v_fma_f32 v125, v121, s34, -v110
	v_mfma_f32_16x16x32_bf16 v[180:183], v[112:115], v[8:11], v[80:83]
	v_add_u32_e32 v3, s9, v211
	v_fma_f32 v120, v128, s34, -v110
	v_fma_f32 v121, v129, s34, -v110
	v_mfma_f32_16x16x32_bf16 v[216:219], v[116:119], v[8:11], v[84:87]
	ds_read_b64 v[84:85], v0 offset:0x800
	ds_read_b64 v[86:87], v2 offset:0x800
	ds_read_b64 v[80:81], v0 offset:0x1000
	v_mfma_f32_16x16x32_bf16 v[104:107], v[92:95], v[4:7], v[60:63]
	ds_read_b64 v[82:83], v2 offset:0x1000
	ds_read_b64 v[76:77], v0 offset:0x1800
	v_max_f32_e32 v0, v122, v123
	v_mfma_f32_16x16x32_bf16 v[92:95], v[116:119], v[4:7], v[72:75]
	v_fma_f32 v118, v126, s34, -v110
	v_fma_f32 v119, v127, s34, -v110
	v_fma_f32 v116, v180, s34, -v110
	v_fma_f32 v117, v181, s34, -v110
	v_max3_f32 v0, v124, v125, v0
	v_mfma_f32_16x16x32_bf16 v[100:103], v[96:99], v[4:7], v[64:67]
	v_max_f32_e32 v126, v118, v119
	v_max_f32_e32 v127, v120, v121
	v_add_u32_e32 v62, s9, v212
	v_mfma_f32_16x16x32_bf16 v[96:99], v[112:115], v[4:7], v[68:71]
	s_setprio 0
	v_fma_f32 v114, v182, s34, -v110
	v_fma_f32 v115, v183, s34, -v110
	ds_read_b64 v[78:79], v2 offset:0x1800
	ds_read_b64 v[72:73], v3 offset:0
	ds_read_b64 v[74:75], v62 offset:0
	ds_read_b64 v[68:69], v3 offset:0x800
	ds_read_b64 v[70:71], v62 offset:0x800
	ds_read_b64 v[64:65], v3 offset:0x1000
	ds_read_b64 v[66:67], v62 offset:0x1000
	ds_read_b64 v[60:61], v3 offset:0x1800
	v_fma_f32 v112, v216, s34, -v110
	v_fma_f32 v113, v217, s34, -v110
	v_fma_f32 v2, v218, s34, -v110
	v_fma_f32 v3, v219, s34, -v110
	v_max3_f32 v0, v0, v126, v127
	v_max_f32_e32 v126, v116, v117
	v_max_f32_e32 v127, v114, v115
	v_max3_f32 v0, v0, v126, v127
	v_max_f32_e32 v126, v112, v113
	v_max_f32_e32 v127, v2, v3
	v_max3_f32 v0, v0, v126, v127
	s_mov_b32 s9, 0x40c00000
	v_cmp_lt_f32_e32 vcc, s9, v0
	ds_read_b64 v[62:63], v62 offset:0x1800
	s_cbranch_vccz .LBB0_2324
	v_mov_b32_e32 v126, v0
	s_nop 1
	v_permlane16_swap_b32_e32 v0, v126
	v_max_f32_e32 v126, v126, v126
	v_max_f32_e32 v0, v0, v0
	v_max_f32_e32 v0, v0, v126
	v_mov_b32_e32 v126, v0
	s_nop 1
	v_permlane32_swap_b32_e32 v0, v126
	v_max3_f32 v0, v0, v126, 0
	v_exp_f32_e64 v126, -v0
	v_pk_add_f32 v[124:125], v[124:125], v[0:1] op_sel_hi:[1,0] neg_lo:[0,1] neg_hi:[0,1]
	v_pk_add_f32 v[122:123], v[122:123], v[0:1] op_sel_hi:[1,0] neg_lo:[0,1] neg_hi:[0,1]
	v_pk_add_f32 v[118:119], v[118:119], v[0:1] op_sel_hi:[1,0] neg_lo:[0,1] neg_hi:[0,1]
	v_pk_add_f32 v[120:121], v[120:121], v[0:1] op_sel_hi:[1,0] neg_lo:[0,1] neg_hi:[0,1]
	v_pk_add_f32 v[116:117], v[116:117], v[0:1] op_sel_hi:[1,0] neg_lo:[0,1] neg_hi:[0,1]
	v_pk_add_f32 v[114:115], v[114:115], v[0:1] op_sel_hi:[1,0] neg_lo:[0,1] neg_hi:[0,1]
	v_pk_add_f32 v[112:113], v[112:113], v[0:1] op_sel_hi:[1,0] neg_lo:[0,1] neg_hi:[0,1]
	v_pk_add_f32 v[2:3], v[2:3], v[0:1] op_sel_hi:[1,0] neg_lo:[0,1] neg_hi:[0,1]
	v_add_f32_e32 v110, v110, v0
	v_mul_f32_e32 v109, v109, v126
	v_pk_mul_f32 v[58:59], v[58:59], v[126:127] op_sel_hi:[1,0]
	v_pk_mul_f32 v[56:57], v[56:57], v[126:127] op_sel_hi:[1,0]
	v_pk_mul_f32 v[50:51], v[50:51], v[126:127] op_sel_hi:[1,0]
	v_pk_mul_f32 v[48:49], v[48:49], v[126:127] op_sel_hi:[1,0]
	v_pk_mul_f32 v[42:43], v[42:43], v[126:127] op_sel_hi:[1,0]
	v_pk_mul_f32 v[40:41], v[40:41], v[126:127] op_sel_hi:[1,0]
	v_pk_mul_f32 v[34:35], v[34:35], v[126:127] op_sel_hi:[1,0]
	v_pk_mul_f32 v[32:33], v[32:33], v[126:127] op_sel_hi:[1,0]
; DEVI float xmax16(float x) { auto r = __builtin_amdgcn_permlane16_swap(__float_as_uint(x), __float_as_uint(x), false, false); return fmaxf(__uint_as_float(r[0]), __uint_as_float(r[1])); }
; DEVI float xmax32(float x) { auto r = __builtin_amdgcn_permlane32_swap(__float_as_uint(x), __float_as_uint(x), false, false); return fmaxf(__uint_as_float(r[0]), __uint_as_float(r[1])); }
; template <int DK, int QB, bool NA>
; DEVI void attn_item(const AttnArgs& a, unsigned char* smem) {
;     ...
;           const f32x2 scv = {a.sc2, a.sc2}, nmv = {-m[qb], -m[qb]};
;           f32x2 t[4][2];
; #pragma unroll
;           for (int kb = 0; kb < 4; ++kb)
; #pragma unroll
;             for (int h = 0; h < 2; ++h) {
;               const f32x2 sv = {s[kb][qb][2 * h], s[kb][qb][2 * h + 1]};
;               t[kb][h] = sv * scv + nmv;
;             }
;           float mx = fmaxf(t[0][0].x, t[0][0].y);
; #pragma unroll
;           for (int kb = 0; kb < 4; ++kb)
; #pragma unroll
;             for (int h = 0; h < 2; ++h) mx = fmaxf(mx, fmaxf(t[kb][h].x, t[kb][h].y));
;           if (j == 0 || __any(mx > 6.f)) {
;             mx = xmax32(xmax16(mx));
;             const float d = (j == 0) ? mx : fmaxf(mx, 0.f);
;             const float alpha = __builtin_amdgcn_exp2f(-d);
;             const f32x2 dv = {d, d};
; #pragma unroll
;             for (int kb = 0; kb < 4; ++kb)
; #pragma unroll
;               for (int h = 0; h < 2; ++h) t[kb][h] -= dv;
;             m[qb] += d;
;             l[qb] *= alpha;
; #pragma unroll
;             for (int db = 0; db < 4; ++db) o[db][qb] *= alpha;
;           }
.LBB0_2324:
	v_mov_b32_e32 v0, v111
	v_fma_f32 v106, v106, s34, -v0
	v_fma_f32 v107, v107, s34, -v0
	v_fma_f32 v126, v104, s34, -v0
	v_fma_f32 v127, v105, s34, -v0
	v_fma_f32 v104, v100, s34, -v0
	v_fma_f32 v105, v101, s34, -v0
	v_fma_f32 v102, v102, s34, -v0
	v_fma_f32 v103, v103, s34, -v0
	v_fma_f32 v100, v96, s34, -v0
	v_fma_f32 v101, v97, s34, -v0
	v_fma_f32 v98, v98, s34, -v0
	v_fma_f32 v99, v99, s34, -v0
	v_fma_f32 v96, v92, s34, -v0
	v_fma_f32 v97, v93, s34, -v0
	v_fma_f32 v92, v94, s34, -v0
	v_fma_f32 v93, v95, s34, -v0
	v_max_f32_e32 v0, v106, v107
	v_max3_f32 v0, v126, v127, v0
	v_max_f32_e32 v94, v104, v105
	v_max_f32_e32 v95, v102, v103
	v_max3_f32 v0, v0, v94, v95
	v_max_f32_e32 v94, v100, v101
	v_max_f32_e32 v95, v98, v99
	v_max3_f32 v0, v0, v94, v95
	v_max_f32_e32 v94, v96, v97
	v_max_f32_e32 v95, v92, v93
	v_max3_f32 v0, v0, v94, v95
	v_cmp_lt_f32_e32 vcc, s9, v0
	s_cbranch_vccz .LBB0_2326
	v_mov_b32_e32 v94, v0
	s_nop 1
	v_permlane16_swap_b32_e32 v0, v94
	v_max_f32_e32 v94, v94, v94
	v_max_f32_e32 v0, v0, v0
	v_max_f32_e32 v0, v0, v94
	v_mov_b32_e32 v94, v0
	s_nop 1
	v_permlane32_swap_b32_e32 v0, v94
	v_max3_f32 v0, v0, v94, 0
	v_exp_f32_e64 v94, -v0
	v_pk_add_f32 v[126:127], v[126:127], v[0:1] op_sel_hi:[1,0] neg_lo:[0,1] neg_hi:[0,1]
	v_pk_add_f32 v[106:107], v[106:107], v[0:1] op_sel_hi:[1,0] neg_lo:[0,1] neg_hi:[0,1]
	v_pk_add_f32 v[104:105], v[104:105], v[0:1] op_sel_hi:[1,0] neg_lo:[0,1] neg_hi:[0,1]
	v_pk_add_f32 v[102:103], v[102:103], v[0:1] op_sel_hi:[1,0] neg_lo:[0,1] neg_hi:[0,1]
	v_pk_add_f32 v[100:101], v[100:101], v[0:1] op_sel_hi:[1,0] neg_lo:[0,1] neg_hi:[0,1]
	v_pk_add_f32 v[98:99], v[98:99], v[0:1] op_sel_hi:[1,0] neg_lo:[0,1] neg_hi:[0,1]
	v_pk_add_f32 v[96:97], v[96:97], v[0:1] op_sel_hi:[1,0] neg_lo:[0,1] neg_hi:[0,1]
	v_pk_add_f32 v[92:93], v[92:93], v[0:1] op_sel_hi:[1,0] neg_lo:[0,1] neg_hi:[0,1]
	v_add_f32_e32 v111, v111, v0
	v_mul_f32_e32 v108, v108, v94
	v_pk_mul_f32 v[54:55], v[54:55], v[94:95] op_sel_hi:[1,0]
	v_pk_mul_f32 v[52:53], v[52:53], v[94:95] op_sel_hi:[1,0]
	v_pk_mul_f32 v[46:47], v[46:47], v[94:95] op_sel_hi:[1,0]
	v_pk_mul_f32 v[44:45], v[44:45], v[94:95] op_sel_hi:[1,0]
	v_pk_mul_f32 v[38:39], v[38:39], v[94:95] op_sel_hi:[1,0]
	v_pk_mul_f32 v[36:37], v[36:37], v[94:95] op_sel_hi:[1,0]
	v_pk_mul_f32 v[30:31], v[30:31], v[94:95] op_sel_hi:[1,0]
	v_pk_mul_f32 v[28:29], v[28:29], v[94:95] op_sel_hi:[1,0]

; template <int DK, int QB, bool NA>
; DEVI void attn_item(const AttnArgs& a, unsigned char* smem) {
;     ...
;         k0[0] = ldsr<0>(a0); k0[1] = ldsr<2048>(a0); k0[2] = ldsr<4096>(a0); k0[3] = ldsr<6144>(a0);
;         k1[0] = ldsr<0>(a1); k1[1] = ldsr<2048>(a1); k1[2] = ldsr<4096>(a1); k1[3] = ldsr<6144>(a1);
;         if constexpr (KS == 3) { k2[0] = ldsr<0>(a2); k2[1] = ldsr<1024>(a2); k2[2] = ldsr<2048>(a2); k2[3] = ldsr<3072>(a2); }
;         if constexpr (KS == 3) asm volatile("s_waitcnt lgkmcnt(8)" : "+v"(k0[0]), "+v"(k0[1]), "+v"(k0[2]), "+v"(k0[3]) :: "memory");
;         else                   asm volatile("s_waitcnt lgkmcnt(4)" : "+v"(k0[0]), "+v"(k0[1]), "+v"(k0[2]), "+v"(k0[3]) :: "memory");
;         __builtin_amdgcn_sched_barrier(0);
; #pragma unroll
;         for (int kb = 0; kb < 4; ++kb)
; #pragma unroll
;           for (int qb = 0; qb < QB; ++qb) s[kb][qb] = __builtin_amdgcn_mfma_f32_16x16x32_bf16(k0[kb], qf[qb][0], s[kb][qb], 0, 0, 0);
;         if constexpr (KS == 3) asm volatile("s_waitcnt lgkmcnt(4)" : "+v"(k1[0]), "+v"(k1[1]), "+v"(k1[2]), "+v"(k1[3]) :: "memory");
;         else                   asm volatile("s_waitcnt lgkmcnt(0)" : "+v"(k1[0]), "+v"(k1[1]), "+v"(k1[2]), "+v"(k1[3]) :: "memory");
;         __builtin_amdgcn_sched_barrier(0);
; #pragma unroll
;         for (int kb = 0; kb < 4; ++kb)
; #pragma unroll
;           for (int qb = 0; qb < QB; ++qb) s[kb][qb] = __builtin_amdgcn_mfma_f32_16x16x32_bf16(k1[kb], qf[qb][1], s[kb][qb], 0, 0, 0);
;         if constexpr (KS == 3) {
;           asm volatile("s_waitcnt lgkmcnt(0)" : "+v"(k2[0]), "+v"(k2[1]), "+v"(k2[2]), "+v"(k2[3]) :: "memory");
;           __builtin_amdgcn_sched_barrier(0);
; #pragma unroll
;           for (int kb = 0; kb < 4; ++kb)
; #pragma unroll
;             for (int qb = 0; qb < QB; ++qb) s[kb][qb] = __builtin_amdgcn_mfma_f32_16x16x32_bf16(k2[kb], qf[qb][2], s[kb][qb], 0, 0, 0);
;         }
;       }
;       u32x2 va[2][4], vbq[2][4];
;       {
;         const unsigned p00 = cur + vb00, p01 = cur + vb01, p10 = cur + vb10, p11 = cur + vb11;
;         va[0][0] = ldsr64<0>(p00); vbq[0][0] = ldsr64<0>(p01); va[0][1] = ldsr64<2048>(p00); vbq[0][1] = ldsr64<2048>(p01);
;         va[0][2] = ldsr64<4096>(p00); vbq[0][2] = ldsr64<4096>(p01); va[0][3] = ldsr64<6144>(p00); vbq[0][3] = ldsr64<6144>(p01);
;     ...
;           const f32x2 scv = {a.sc2, a.sc2}, nmv = {-m[qb], -m[qb]};
.LBB0_2327:
	s_or_b64 exec, exec, s[2:3]
	s_waitcnt vmcnt(0)
	s_waitcnt lgkmcnt(0)
	s_barrier
	s_and_saveexec_b64 s[2:3], s[0:1]
	s_cbranch_execz .LBB0_2337
	s_add_i32 s0, s8, 1
	s_mul_i32 s1, s0, 0x5000
	s_cmp_lg_u32 s0, 3
	s_cselect_b32 s0, s1, 0
	v_or_b32_e32 v0, s0, v213
	ds_read_b128 v[60:63], v0 offset:0
	ds_read_b128 v[64:67], v0 offset:0x800
	ds_read_b128 v[68:71], v0 offset:0x1000
	ds_read_b128 v[72:75], v0 offset:0x1800
	v_or_b32_e32 v2, s0, v214
	v_add_u32_e32 v3, s0, v215
	ds_read_b128 v[76:79], v2 offset:0
	ds_read_b128 v[80:83], v2 offset:0x800
	ds_read_b128 v[84:87], v2 offset:0x1000
	ds_read_b128 v[88:91], v2 offset:0x1800
	ds_read_b128 v[92:95], v3 offset:0
	ds_read_b128 v[96:99], v3 offset:0x400
	ds_read_b128 v[100:103], v3 offset:0x800
	ds_read_b128 v[104:107], v3 offset:0xc00
	s_waitcnt lgkmcnt(8)
	s_nop 0
	s_setprio 1
	v_mfma_f32_16x16x32_bf16 v[24:27], v[60:63], v[24:27], 0
	s_waitcnt lgkmcnt(4)
	v_mfma_f32_16x16x32_bf16 v[20:23], v[60:63], v[20:23], 0
	v_mfma_f32_16x16x32_bf16 v[16:19], v[76:79], v[16:19], v[24:27]
	s_waitcnt lgkmcnt(0)
	v_mfma_f32_16x16x32_bf16 v[12:15], v[76:79], v[12:15], v[20:23]
	v_mfma_f32_16x16x32_bf16 v[74:77], v[92:95], v[8:11], v[16:19]
	v_add_u32_e32 v2, s0, v210
	v_add_u32_e32 v3, s0, v211
	s_nop 1
	v_add_u32_e32 v26, s0, v212
	v_add_u32_e32 v0, s0, v209
	ds_read_b64 v[64:65], v0 offset:0
	v_mfma_f32_16x16x32_bf16 v[68:71], v[92:95], v[4:7], v[12:15]
	s_setprio 0
	ds_read_b64 v[66:67], v2 offset:0
	ds_read_b64 v[60:61], v0 offset:0x800
	ds_read_b64 v[62:63], v2 offset:0x800
	ds_read_b64 v[22:23], v0 offset:0x1000
	ds_read_b64 v[24:25], v2 offset:0x1000
	ds_read_b64 v[18:19], v0 offset:0x1800
	ds_read_b64 v[20:21], v2 offset:0x1800
	ds_read_b64 v[14:15], v3 offset:0
	ds_read_b64 v[16:17], v26 offset:0
	ds_read_b64 v[10:11], v3 offset:0x800
	ds_read_b64 v[12:13], v26 offset:0x800
	ds_read_b64 v[6:7], v3 offset:0x1000
	ds_read_b64 v[8:9], v26 offset:0x1000
	ds_read_b64 v[2:3], v3 offset:0x1800
	ds_read_b64 v[4:5], v26 offset:0x1800
	s_nop 0
	v_fma_f32 v74, v74, s34, -v110
	v_fma_f32 v75, v75, s34, -v110
	v_fma_f32 v72, v76, s34, -v110
	v_fma_f32 v73, v77, s34, -v110
	v_sub_f32_e32 v26, 0xefede2e1, v110
	v_max_f32_e32 v0, v74, v75
	v_max_f32_e32 v27, v72, v73
	v_max_f32_e32 v76, v26, v26
	v_max3_f32 v0, v0, v27, v76
	s_mov_b32 s0, 0x40c00000
	v_mov_b32_e32 v27, v26
	v_cmp_lt_f32_e32 vcc, s0, v0
	s_cbranch_vccz .LBB0_2330
	v_mov_b32_e32 v76, v0
	s_nop 1
	v_permlane16_swap_b32_e32 v0, v76
	v_max_f32_e32 v76, v76, v76
	v_max_f32_e32 v0, v0, v0
	v_max_f32_e32 v0, v0, v76
	v_mov_b32_e32 v76, v0
	s_nop 1
	v_permlane32_swap_b32_e32 v0, v76
	v_max3_f32 v0, v0, v76, 0
	v_exp_f32_e64 v76, -v0
	v_pk_add_f32 v[74:75], v[74:75], v[0:1] op_sel_hi:[1,0] neg_lo:[0,1] neg_hi:[0,1]
	v_pk_add_f32 v[72:73], v[72:73], v[0:1] op_sel_hi:[1,0] neg_lo:[0,1] neg_hi:[0,1]
	v_pk_add_f32 v[26:27], v[26:27], v[0:1] op_sel_hi:[1,0] neg_lo:[0,1] neg_hi:[0,1]
	v_mul_f32_e32 v109, v109, v76
	v_pk_mul_f32 v[58:59], v[58:59], v[76:77] op_sel_hi:[1,0]
	v_pk_mul_f32 v[56:57], v[56:57], v[76:77] op_sel_hi:[1,0]
	v_pk_mul_f32 v[50:51], v[50:51], v[76:77] op_sel_hi:[1,0]
	v_pk_mul_f32 v[48:49], v[48:49], v[76:77] op_sel_hi:[1,0]
	v_pk_mul_f32 v[42:43], v[42:43], v[76:77] op_sel_hi:[1,0]
	v_pk_mul_f32 v[40:41], v[40:41], v[76:77] op_sel_hi:[1,0]
	v_pk_mul_f32 v[34:35], v[34:35], v[76:77] op_sel_hi:[1,0]
	v_pk_mul_f32 v[32:33], v[32:33], v[76:77] op_sel_hi:[1,0]
.LBB0_2330:
	v_mov_b32_e32 v0, v111
	v_fma_f32 v68, v68, s34, -v0
	v_fma_f32 v69, v69, s34, -v0
	v_fma_f32 v76, v70, s34, -v0
	v_fma_f32 v77, v71, s34, -v0
	v_sub_f32_e32 v70, 0xefede2e1, v111
	v_max_f32_e32 v0, v68, v69
	v_max_f32_e32 v71, v76, v77
	v_max_f32_e32 v78, v70, v70
	v_max3_f32 v0, v0, v71, v78
	v_mov_b32_e32 v71, v70
	v_cmp_lt_f32_e32 vcc, s0, v0
	s_cbranch_vccz .LBB0_2332
	v_mov_b32_e32 v78, v0
	s_nop 1
	v_permlane16_swap_b32_e32 v0, v78
	v_max_f32_e32 v78, v78, v78
	v_max_f32_e32 v0, v0, v0
	v_max_f32_e32 v0, v0, v78
	v_mov_b32_e32 v78, v0
	s_nop 1
	v_permlane32_swap_b32_e32 v0, v78
	v_max3_f32 v0, v0, v78, 0
	v_exp_f32_e64 v78, -v0
	v_pk_add_f32 v[68:69], v[68:69], v[0:1] op_sel_hi:[1,0] neg_lo:[0,1] neg_hi:[0,1]
	v_pk_add_f32 v[76:77], v[76:77], v[0:1] op_sel_hi:[1,0] neg_lo:[0,1] neg_hi:[0,1]
	v_pk_add_f32 v[70:71], v[70:71], v[0:1] op_sel_hi:[1,0] neg_lo:[0,1] neg_hi:[0,1]
	v_mul_f32_e32 v108, v108, v78
	v_pk_mul_f32 v[54:55], v[54:55], v[78:79] op_sel_hi:[1,0]
	v_pk_mul_f32 v[52:53], v[52:53], v[78:79] op_sel_hi:[1,0]
	v_pk_mul_f32 v[46:47], v[46:47], v[78:79] op_sel_hi:[1,0]
	v_pk_mul_f32 v[44:45], v[44:45], v[78:79] op_sel_hi:[1,0]
	v_pk_mul_f32 v[38:39], v[38:39], v[78:79] op_sel_hi:[1,0]
	v_pk_mul_f32 v[36:37], v[36:37], v[78:79] op_sel_hi:[1,0]
	v_pk_mul_f32 v[30:31], v[30:31], v[78:79] op_sel_hi:[1,0]
	v_pk_mul_f32 v[28:29], v[28:29], v[78:79] op_sel_hi:[1,0]
